# v60 + half of the next tile's 4x4x4 MFMAs issued inside the second half of the current recurrence (into already-consumed bu registers)
# baseline (speedup 1.0000x reference)
; #define LAS __attribute__((address_space(3)))
; __device__ __forceinline__ unsigned pk2(float lo, float hi) { f32x2 v = {lo, hi}; nbf2 r = __builtin_convertvector(v, nbf2); return __builtin_bit_cast(unsigned, r); }
; #define WAVE_LDS_FENCE() asm volatile("s_waitcnt lgkmcnt(0)" ::: "memory")
; __device__ __forceinline__ float bf_at(const u32x4& lo, const u32x4& hi, int r) { const unsigned w = (r < 8 ? lo : hi)[(r & 7) >> 1]; return (r & 1) ? bf_hi(w) : bf_lo(w); }
; __device__ __forceinline__ void s5_out_phase(LAS unsigned char* lds, const bf16_t* UZ, const unsigned char* ws, const float* dskip, bf16_t* YG) {
;     ...
;         for (int mm = 0; mm < 4; ++mm) {
;             const int mf = mm, mb = 3 - mm;
; #pragma unroll
;             for (int nt = 0; nt < 8; ++nt) {
;                 const f32x4 z = {0.f, 0.f, 0.f, 0.f};
;                 const f32x4 cf = __builtin_amdgcn_mfma_f32_16x16x16bf16_1k(Uf[mf], Bf[0][nt], z, 0, 0, 0);
;                 const f32x4 cb = __builtin_amdgcn_mfma_f32_16x16x16bf16_1k(Uf[mb], Bf[1][nt], z, 0, 0, 0);
;                 u32x2 wf, wb; wf.x = pk2(cf[0], cf[1]); wf.y = pk2(cf[2], cf[3]); wb.x = pk2(cb[0], cb[1]); wb.y = pk2(cb[2], cb[3]);
;                 *(LAS u32x2*)(wl + nt * 640 + wofs) = wf;
;                 *(LAS u32x2*)(wl + BUT_BYTES + nt * 640 + wofs) = wb;
;             }
;             WAVE_LDS_FENCE();
;             const LAS unsigned char* rp = wl + lane * 80;
;             const u32x4 fre0 = *(const LAS u32x4*)(rp), fre1 = *(const LAS u32x4*)(rp + 16), fim0 = *(const LAS u32x4*)(rp + 32), fim1 = *(const LAS u32x4*)(rp + 48);
;             const u32x4 bre0 = *(const LAS u32x4*)(rp + BUT_BYTES), bre1 = *(const LAS u32x4*)(rp + BUT_BYTES + 16), bim0 = *(const LAS u32x4*)(rp + BUT_BYTES + 32), bim1 = *(const LAS u32x4*)(rp + BUT_BYTES + 48);
;             LAS unsigned char* xf = wl + 2 * BUT_BYTES; LAS unsigned char* xbk = xf + XB_BYTES;
; #pragma unroll
;             for (int rr = 0; rr < 16; ++rr) {
;                 const int r = rr, rb = 15 - rr;
;                 { const f32x2 bb = {bf_at(fre0, fre1, r), bf_at(fim0, fim1, r)};
;                   const f32x2 n2 = cmac((f32x2){xfr, xfi}, (f32x2){ap[0].x, ap[0].x}, (f32x2){-ap[0].y, ap[0].y}, bb); xfr = n2.x; xfi = n2.y;
.LBB0_755:
	v_mov_b32_e32 v114, v44
	v_mov_b32_e32 v119, v45
	v_mov_b32_e32 v121, v46
	v_mov_b32_e32 v127, v47
	v_mfma_f32_4x4x4_16b_bf16 v[188:191], v[172:173], v[60:61], 0 cbsz:4 abid:0
	v_mfma_f32_4x4x4_16b_bf16 v[194:197], v[172:173], v[68:69], 0 cbsz:4 abid:0
	v_mfma_f32_4x4x4_16b_bf16 v[198:201], v[172:173], v[60:61], 0 cbsz:4 abid:1
	v_mfma_f32_4x4x4_16b_bf16 v[202:205], v[172:173], v[68:69], 0 cbsz:4 abid:1
	v_mfma_f32_4x4x4_16b_bf16 v[206:209], v[172:173], v[60:61], 0 cbsz:4 abid:2
	v_mfma_f32_4x4x4_16b_bf16 v[210:213], v[172:173], v[68:69], 0 cbsz:4 abid:2
	v_mfma_f32_4x4x4_16b_bf16 v[214:217], v[172:173], v[60:61], 0 cbsz:4 abid:3
	v_mfma_f32_4x4x4_16b_bf16 v[218:221], v[172:173], v[68:69], 0 cbsz:4 abid:3
	v_mfma_f32_4x4x4_16b_bf16 v[222:225], v[116:117], v[76:77], 0 cbsz:4 abid:0
	v_mfma_f32_4x4x4_16b_bf16 v[226:229], v[116:117], v[84:85], 0 cbsz:4 abid:0
	v_mfma_f32_4x4x4_16b_bf16 v[230:233], v[116:117], v[76:77], 0 cbsz:4 abid:1
	v_mfma_f32_4x4x4_16b_bf16 v[234:237], v[116:117], v[84:85], 0 cbsz:4 abid:1
	v_mfma_f32_4x4x4_16b_bf16 v[238:241], v[116:117], v[76:77], 0 cbsz:4 abid:2
	v_mfma_f32_4x4x4_16b_bf16 v[242:245], v[116:117], v[84:85], 0 cbsz:4 abid:2
	v_mfma_f32_4x4x4_16b_bf16 v[246:249], v[116:117], v[76:77], 0 cbsz:4 abid:3
	v_mfma_f32_4x4x4_16b_bf16 v[250:253], v[116:117], v[84:85], 0 cbsz:4 abid:3
	v_mfma_f32_4x4x4_16b_bf16 v[188:191], v[172:173], v[62:63], v[188:191] cbsz:4 abid:4
	v_mfma_f32_4x4x4_16b_bf16 v[194:197], v[172:173], v[70:71], v[194:197] cbsz:4 abid:4
	v_mfma_f32_4x4x4_16b_bf16 v[198:201], v[172:173], v[62:63], v[198:201] cbsz:4 abid:5
	v_mfma_f32_4x4x4_16b_bf16 v[202:205], v[172:173], v[70:71], v[202:205] cbsz:4 abid:5
	v_mfma_f32_4x4x4_16b_bf16 v[206:209], v[172:173], v[62:63], v[206:209] cbsz:4 abid:6
	v_mfma_f32_4x4x4_16b_bf16 v[210:213], v[172:173], v[70:71], v[210:213] cbsz:4 abid:6
	v_mfma_f32_4x4x4_16b_bf16 v[214:217], v[172:173], v[62:63], v[214:217] cbsz:4 abid:7
	v_mfma_f32_4x4x4_16b_bf16 v[218:221], v[172:173], v[70:71], v[218:221] cbsz:4 abid:7
	v_mfma_f32_4x4x4_16b_bf16 v[222:225], v[116:117], v[78:79], v[222:225] cbsz:4 abid:4
	v_mfma_f32_4x4x4_16b_bf16 v[226:229], v[116:117], v[86:87], v[226:229] cbsz:4 abid:4
	v_mfma_f32_4x4x4_16b_bf16 v[230:233], v[116:117], v[78:79], v[230:233] cbsz:4 abid:5
	v_mfma_f32_4x4x4_16b_bf16 v[234:237], v[116:117], v[86:87], v[234:237] cbsz:4 abid:5
	v_mfma_f32_4x4x4_16b_bf16 v[238:241], v[116:117], v[78:79], v[238:241] cbsz:4 abid:6
	v_mfma_f32_4x4x4_16b_bf16 v[242:245], v[116:117], v[86:87], v[242:245] cbsz:4 abid:6
	v_mfma_f32_4x4x4_16b_bf16 v[246:249], v[116:117], v[78:79], v[246:249] cbsz:4 abid:7
	v_mfma_f32_4x4x4_16b_bf16 v[250:253], v[116:117], v[86:87], v[250:253] cbsz:4 abid:7
	v_mfma_f32_4x4x4_16b_bf16 v[188:191], v[172:173], v[64:65], v[188:191] cbsz:4 abid:8
	v_mfma_f32_4x4x4_16b_bf16 v[194:197], v[172:173], v[72:73], v[194:197] cbsz:4 abid:8
	v_mfma_f32_4x4x4_16b_bf16 v[198:201], v[172:173], v[64:65], v[198:201] cbsz:4 abid:9
	v_mfma_f32_4x4x4_16b_bf16 v[202:205], v[172:173], v[72:73], v[202:205] cbsz:4 abid:9
	v_mfma_f32_4x4x4_16b_bf16 v[206:209], v[172:173], v[64:65], v[206:209] cbsz:4 abid:10
	v_mfma_f32_4x4x4_16b_bf16 v[210:213], v[172:173], v[72:73], v[210:213] cbsz:4 abid:10
	v_mfma_f32_4x4x4_16b_bf16 v[214:217], v[172:173], v[64:65], v[214:217] cbsz:4 abid:11
	v_mfma_f32_4x4x4_16b_bf16 v[218:221], v[172:173], v[72:73], v[218:221] cbsz:4 abid:11
	v_mfma_f32_4x4x4_16b_bf16 v[222:225], v[116:117], v[80:81], v[222:225] cbsz:4 abid:8
	v_mfma_f32_4x4x4_16b_bf16 v[226:229], v[116:117], v[88:89], v[226:229] cbsz:4 abid:8
	v_mfma_f32_4x4x4_16b_bf16 v[230:233], v[116:117], v[80:81], v[230:233] cbsz:4 abid:9
	v_mfma_f32_4x4x4_16b_bf16 v[234:237], v[116:117], v[88:89], v[234:237] cbsz:4 abid:9
	v_mfma_f32_4x4x4_16b_bf16 v[238:241], v[116:117], v[80:81], v[238:241] cbsz:4 abid:10
	v_mfma_f32_4x4x4_16b_bf16 v[242:245], v[116:117], v[88:89], v[242:245] cbsz:4 abid:10
	v_mfma_f32_4x4x4_16b_bf16 v[246:249], v[116:117], v[80:81], v[246:249] cbsz:4 abid:11
	v_mfma_f32_4x4x4_16b_bf16 v[250:253], v[116:117], v[88:89], v[250:253] cbsz:4 abid:11
	v_mfma_f32_4x4x4_16b_bf16 v[188:191], v[172:173], v[66:67], v[188:191] cbsz:4 abid:12
	v_mfma_f32_4x4x4_16b_bf16 v[194:197], v[172:173], v[74:75], v[194:197] cbsz:4 abid:12
	v_mfma_f32_4x4x4_16b_bf16 v[198:201], v[172:173], v[66:67], v[198:201] cbsz:4 abid:13
	v_mfma_f32_4x4x4_16b_bf16 v[202:205], v[172:173], v[74:75], v[202:205] cbsz:4 abid:13
	v_mfma_f32_4x4x4_16b_bf16 v[206:209], v[172:173], v[66:67], v[206:209] cbsz:4 abid:14
	v_mfma_f32_4x4x4_16b_bf16 v[210:213], v[172:173], v[74:75], v[210:213] cbsz:4 abid:14
	v_mfma_f32_4x4x4_16b_bf16 v[214:217], v[172:173], v[66:67], v[214:217] cbsz:4 abid:15
	v_mfma_f32_4x4x4_16b_bf16 v[218:221], v[172:173], v[74:75], v[218:221] cbsz:4 abid:15
	v_mfma_f32_4x4x4_16b_bf16 v[222:225], v[116:117], v[82:83], v[222:225] cbsz:4 abid:12
	v_mfma_f32_4x4x4_16b_bf16 v[226:229], v[116:117], v[90:91], v[226:229] cbsz:4 abid:12
	v_mfma_f32_4x4x4_16b_bf16 v[230:233], v[116:117], v[82:83], v[230:233] cbsz:4 abid:13
	v_mfma_f32_4x4x4_16b_bf16 v[234:237], v[116:117], v[90:91], v[234:237] cbsz:4 abid:13
	v_mfma_f32_4x4x4_16b_bf16 v[238:241], v[116:117], v[82:83], v[238:241] cbsz:4 abid:14
	v_mfma_f32_4x4x4_16b_bf16 v[242:245], v[116:117], v[90:91], v[242:245] cbsz:4 abid:14
	v_mfma_f32_4x4x4_16b_bf16 v[246:249], v[116:117], v[82:83], v[246:249] cbsz:4 abid:15
	v_mfma_f32_4x4x4_16b_bf16 v[250:253], v[116:117], v[90:91], v[250:253] cbsz:4 abid:15
	v_fma_f32 v188, v150, v114, v188
	v_fma_f32 v194, v150, v119, v194
	v_fma_f32 v188, v16, v119, v188
	v_fma_f32 v194, v17, v114, v194
; #define LAS __attribute__((address_space(3)))
; __device__ __forceinline__ unsigned pk2(float lo, float hi) { f32x2 v = {lo, hi}; nbf2 r = __builtin_convertvector(v, nbf2); return __builtin_bit_cast(unsigned, r); }
; __device__ __forceinline__ float bf_at(const u32x4& lo, const u32x4& hi, int r) { const unsigned w = (r < 8 ? lo : hi)[(r & 7) >> 1]; return (r & 1) ? bf_hi(w) : bf_lo(w); }
; __device__ __forceinline__ void s5_out_phase(LAS unsigned char* lds, const bf16_t* UZ, const unsigned char* ws, const float* dskip, bf16_t* YG) {
;     ...
; #pragma unroll
;             for (int nt = 0; nt < 8; ++nt) {
;                 const f32x4 z = {0.f, 0.f, 0.f, 0.f};
;                 const f32x4 cf = __builtin_amdgcn_mfma_f32_16x16x16bf16_1k(Uf[mf], Bf[0][nt], z, 0, 0, 0);
;                 const f32x4 cb = __builtin_amdgcn_mfma_f32_16x16x16bf16_1k(Uf[mb], Bf[1][nt], z, 0, 0, 0);
;                 u32x2 wf, wb; wf.x = pk2(cf[0], cf[1]); wf.y = pk2(cf[2], cf[3]); wb.x = pk2(cb[0], cb[1]); wb.y = pk2(cb[2], cb[3]);
;                 *(LAS u32x2*)(wl + nt * 640 + wofs) = wf;
;                 *(LAS u32x2*)(wl + BUT_BYTES + nt * 640 + wofs) = wb;
;             }
;     ...
; #pragma unroll
;             for (int rr = 0; rr < 16; ++rr) {
;                 const int r = rr, rb = 15 - rr;
;                 { const f32x2 bb = {bf_at(fre0, fre1, r), bf_at(fim0, fim1, r)};
;                   const f32x2 n2 = cmac((f32x2){xfr, xfi}, (f32x2){ap[0].x, ap[0].x}, (f32x2){-ap[0].y, ap[0].y}, bb); xfr = n2.x; xfi = n2.y;
;                   *(LAS unsigned*)(xf + r * XB_PITCH + lane * 4) = pk2(n2.x, n2.y); }
;                 { const f32x2 bb = {bf_at(bre0, bre1, rb), bf_at(bim0, bim1, rb)};
;                   const f32x2 n2 = cmac((f32x2){xbr, xbi}, (f32x2){ap[1].x, ap[1].x}, (f32x2){-ap[1].y, ap[1].y}, bb); xbr = n2.x; xbi = n2.y;
;                   *(LAS unsigned*)(xbk + rb * XB_PITCH + lane * 4) = pk2(n2.x, n2.y); }
;             }
	v_fma_f32 v249, v152, v121, v249
	v_fma_f32 v253, v152, v127, v253
	v_fma_f32 v249, v36, v127, v249
	v_fma_f32 v253, v37, v121, v253
	v_cvt_pk_bf16_f32 v128, v188, v194
	v_cvt_pk_bf16_f32 v136, v249, v253
	v_add_u32_e32 v193, 0x2800, v103
	v_add_u32_e32 v254, 0x45c0, v103
	v_fma_f32 v189, v150, v188, v189
	v_fma_f32 v195, v150, v194, v195
	v_fma_f32 v189, v16, v194, v189
	v_fma_f32 v195, v17, v188, v195
	v_fma_f32 v248, v152, v249, v248
	v_fma_f32 v252, v152, v253, v252
	v_fma_f32 v248, v36, v253, v248
	v_fma_f32 v252, v37, v249, v252
	v_cvt_pk_bf16_f32 v131, v189, v195
	v_cvt_pk_bf16_f32 v139, v248, v252
	ds_write2_b32 v193, v128, v131 offset0:0 offset1:68
	ds_write2_b32 v254, v139, v136 offset0:136 offset1:204
	v_fma_f32 v190, v150, v189, v190
	v_fma_f32 v196, v150, v195, v196
	v_fma_f32 v190, v16, v195, v190
	v_fma_f32 v196, v17, v189, v196
	v_fma_f32 v247, v152, v248, v247
	v_fma_f32 v251, v152, v252, v251
	v_fma_f32 v247, v36, v252, v247
	v_fma_f32 v251, v37, v248, v251
	v_cvt_pk_bf16_f32 v132, v190, v196
	v_cvt_pk_bf16_f32 v143, v247, v251
	v_fma_f32 v191, v150, v190, v191
	v_fma_f32 v197, v150, v196, v197
	v_fma_f32 v191, v16, v196, v191
	v_fma_f32 v197, v17, v190, v197
	v_fma_f32 v246, v152, v247, v246
	v_fma_f32 v250, v152, v251, v250
	v_fma_f32 v246, v36, v251, v246
	v_fma_f32 v250, v37, v247, v250
	v_cvt_pk_bf16_f32 v135, v191, v197
	v_cvt_pk_bf16_f32 v187, v246, v250
	ds_write2_b32 v193, v132, v135 offset0:136 offset1:204
	ds_write2_b32 v254, v187, v143 offset0:0 offset1:68
	v_fma_f32 v198, v150, v191, v198
	v_fma_f32 v202, v150, v197, v202
	v_fma_f32 v198, v16, v197, v198
	v_fma_f32 v202, v17, v191, v202
	v_fma_f32 v241, v152, v246, v241
	v_fma_f32 v245, v152, v250, v245
	v_fma_f32 v241, v36, v250, v241
	v_fma_f32 v245, v37, v246, v245
	v_cvt_pk_bf16_f32 v128, v198, v202
	v_cvt_pk_bf16_f32 v136, v241, v245
	v_add_u32_e32 v193, 0x2c40, v103
	v_add_u32_e32 v254, 0x4180, v103
	v_fma_f32 v199, v150, v198, v199
	v_fma_f32 v203, v150, v202, v203
	v_mfma_f32_4x4x4_16b_bf16 v[188:191], v[170:171], v[60:61], 0 cbsz:4 abid:0
	v_fma_f32 v199, v16, v202, v199
	v_fma_f32 v203, v17, v198, v203
	v_mfma_f32_4x4x4_16b_bf16 v[194:197], v[170:171], v[68:69], 0 cbsz:4 abid:0
	v_fma_f32 v240, v152, v241, v240
	v_fma_f32 v244, v152, v245, v244
	v_mfma_f32_4x4x4_16b_bf16 v[246:249], v[168:169], v[76:77], 0 cbsz:4 abid:3
	v_fma_f32 v240, v36, v245, v240
	v_fma_f32 v244, v37, v241, v244
	v_mfma_f32_4x4x4_16b_bf16 v[250:253], v[168:169], v[84:85], 0 cbsz:4 abid:3
	v_cvt_pk_bf16_f32 v131, v199, v203
	v_cvt_pk_bf16_f32 v139, v240, v244
	ds_write2_b32 v193, v128, v131 offset0:0 offset1:68
	ds_write2_b32 v254, v139, v136 offset0:136 offset1:204
	v_mfma_f32_4x4x4_16b_bf16 v[188:191], v[170:171], v[62:63], v[188:191] cbsz:4 abid:4
	v_mfma_f32_4x4x4_16b_bf16 v[194:197], v[170:171], v[70:71], v[194:197] cbsz:4 abid:4
	v_fma_f32 v200, v150, v199, v200
	v_fma_f32 v204, v150, v203, v204
	v_mfma_f32_4x4x4_16b_bf16 v[246:249], v[168:169], v[78:79], v[246:249] cbsz:4 abid:7
	v_fma_f32 v200, v16, v203, v200
	v_fma_f32 v204, v17, v199, v204
	v_mfma_f32_4x4x4_16b_bf16 v[250:253], v[168:169], v[86:87], v[250:253] cbsz:4 abid:7
	v_fma_f32 v239, v152, v240, v239
	v_fma_f32 v243, v152, v244, v243
	v_mfma_f32_4x4x4_16b_bf16 v[188:191], v[170:171], v[64:65], v[188:191] cbsz:4 abid:8
	v_fma_f32 v239, v36, v244, v239
	v_fma_f32 v243, v37, v240, v243
	v_mfma_f32_4x4x4_16b_bf16 v[194:197], v[170:171], v[72:73], v[194:197] cbsz:4 abid:8
	v_cvt_pk_bf16_f32 v132, v200, v204
	v_cvt_pk_bf16_f32 v143, v239, v243
	v_mfma_f32_4x4x4_16b_bf16 v[246:249], v[168:169], v[80:81], v[246:249] cbsz:4 abid:11
	v_mfma_f32_4x4x4_16b_bf16 v[250:253], v[168:169], v[88:89], v[250:253] cbsz:4 abid:11
	v_fma_f32 v201, v150, v200, v201
	v_fma_f32 v205, v150, v204, v205
	v_mfma_f32_4x4x4_16b_bf16 v[188:191], v[170:171], v[66:67], v[188:191] cbsz:4 abid:12
	v_fma_f32 v201, v16, v204, v201
	v_fma_f32 v205, v17, v200, v205
	v_mfma_f32_4x4x4_16b_bf16 v[194:197], v[170:171], v[74:75], v[194:197] cbsz:4 abid:12
	v_fma_f32 v238, v152, v239, v238
	v_fma_f32 v242, v152, v243, v242
	v_mfma_f32_4x4x4_16b_bf16 v[246:249], v[168:169], v[82:83], v[246:249] cbsz:4 abid:15
	v_fma_f32 v238, v36, v243, v238
	v_fma_f32 v242, v37, v239, v242
	v_mfma_f32_4x4x4_16b_bf16 v[250:253], v[168:169], v[90:91], v[250:253] cbsz:4 abid:15
	v_cvt_pk_bf16_f32 v135, v201, v205
	v_cvt_pk_bf16_f32 v187, v238, v242
	ds_write2_b32 v193, v132, v135 offset0:136 offset1:204
	ds_write2_b32 v254, v187, v143 offset0:0 offset1:68
	v_fma_f32 v206, v150, v201, v206
	v_fma_f32 v210, v150, v205, v210
	v_fma_f32 v206, v16, v205, v206
	v_fma_f32 v210, v17, v201, v210
	v_fma_f32 v233, v152, v238, v233
	v_fma_f32 v237, v152, v242, v237
	v_fma_f32 v233, v36, v242, v233
	v_fma_f32 v237, v37, v238, v237
	v_cvt_pk_bf16_f32 v128, v206, v210
	v_cvt_pk_bf16_f32 v136, v233, v237
	v_add_u32_e32 v193, 0x3080, v103
	v_add_u32_e32 v254, 0x3d40, v103
	v_fma_f32 v207, v150, v206, v207
	v_fma_f32 v211, v150, v210, v211
	v_mfma_f32_4x4x4_16b_bf16 v[198:201], v[170:171], v[60:61], 0 cbsz:4 abid:1
	v_fma_f32 v207, v16, v210, v207
	v_fma_f32 v211, v17, v206, v211
	v_mfma_f32_4x4x4_16b_bf16 v[202:205], v[170:171], v[68:69], 0 cbsz:4 abid:1
	v_fma_f32 v232, v152, v233, v232
	v_fma_f32 v236, v152, v237, v236
	v_mfma_f32_4x4x4_16b_bf16 v[238:241], v[168:169], v[76:77], 0 cbsz:4 abid:2
	v_fma_f32 v232, v36, v237, v232
	v_fma_f32 v236, v37, v233, v236
	v_mfma_f32_4x4x4_16b_bf16 v[242:245], v[168:169], v[84:85], 0 cbsz:4 abid:2
	v_cvt_pk_bf16_f32 v131, v207, v211
	v_cvt_pk_bf16_f32 v139, v232, v236
	ds_write2_b32 v193, v128, v131 offset0:0 offset1:68
; #define LAS __attribute__((address_space(3)))
; __device__ __forceinline__ unsigned pk2(float lo, float hi) { f32x2 v = {lo, hi}; nbf2 r = __builtin_convertvector(v, nbf2); return __builtin_bit_cast(unsigned, r); }
; #define WAVE_LDS_FENCE() asm volatile("s_waitcnt lgkmcnt(0)" ::: "memory")
; __device__ __forceinline__ float bf_at(const u32x4& lo, const u32x4& hi, int r) { const unsigned w = (r < 8 ? lo : hi)[(r & 7) >> 1]; return (r & 1) ? bf_hi(w) : bf_lo(w); }
; __device__ __forceinline__ void s5_out_phase(LAS unsigned char* lds, const bf16_t* UZ, const unsigned char* ws, const float* dskip, bf16_t* YG) {
;     ...
; #pragma unroll
;             for (int rr = 0; rr < 16; ++rr) {
;                 const int r = rr, rb = 15 - rr;
;                 { const f32x2 bb = {bf_at(fre0, fre1, r), bf_at(fim0, fim1, r)};
;                   const f32x2 n2 = cmac((f32x2){xfr, xfi}, (f32x2){ap[0].x, ap[0].x}, (f32x2){-ap[0].y, ap[0].y}, bb); xfr = n2.x; xfi = n2.y;
;                   *(LAS unsigned*)(xf + r * XB_PITCH + lane * 4) = pk2(n2.x, n2.y); }
;                 { const f32x2 bb = {bf_at(bre0, bre1, rb), bf_at(bim0, bim1, rb)};
;                   const f32x2 n2 = cmac((f32x2){xbr, xbi}, (f32x2){ap[1].x, ap[1].x}, (f32x2){-ap[1].y, ap[1].y}, bb); xbr = n2.x; xbi = n2.y;
;                   *(LAS unsigned*)(xbk + rb * XB_PITCH + lane * 4) = pk2(n2.x, n2.y); }
;             }
;             WAVE_LDS_FENCE();
; #pragma unroll
;             for (int ks = 0; ks < 4; ++ks) {
;                 const bf16x8 Xf = *(const LAS bf16x8*)(xf + fr * XB_PITCH + (8 * fq + 32 * ks) * 2);
;                 const bf16x8 Xb = *(const LAS bf16x8*)(xbk + fr * XB_PITCH + (8 * fq + 32 * ks) * 2);
;                 accY[mf] = __builtin_amdgcn_mfma_f32_16x16x32_bf16(Cf[0][ks], Xf, accY[mf], 0, 0, 0);
;                 accY[mb] = __builtin_amdgcn_mfma_f32_16x16x32_bf16(Cf[1][ks], Xb, accY[mb], 0, 0, 0);
;             }
	ds_write2_b32 v254, v139, v136 offset0:136 offset1:204
	v_mfma_f32_4x4x4_16b_bf16 v[198:201], v[170:171], v[62:63], v[198:201] cbsz:4 abid:5
	v_mfma_f32_4x4x4_16b_bf16 v[202:205], v[170:171], v[70:71], v[202:205] cbsz:4 abid:5
	v_fma_f32 v208, v150, v207, v208
	v_fma_f32 v212, v150, v211, v212
	v_mfma_f32_4x4x4_16b_bf16 v[238:241], v[168:169], v[78:79], v[238:241] cbsz:4 abid:6
	v_fma_f32 v208, v16, v211, v208
	v_fma_f32 v212, v17, v207, v212
	v_mfma_f32_4x4x4_16b_bf16 v[242:245], v[168:169], v[86:87], v[242:245] cbsz:4 abid:6
	v_fma_f32 v231, v152, v232, v231
	v_fma_f32 v235, v152, v236, v235
	v_mfma_f32_4x4x4_16b_bf16 v[198:201], v[170:171], v[64:65], v[198:201] cbsz:4 abid:9
	v_fma_f32 v231, v36, v236, v231
	v_fma_f32 v235, v37, v232, v235
	v_mfma_f32_4x4x4_16b_bf16 v[202:205], v[170:171], v[72:73], v[202:205] cbsz:4 abid:9
	v_cvt_pk_bf16_f32 v132, v208, v212
	v_cvt_pk_bf16_f32 v143, v231, v235
	v_mfma_f32_4x4x4_16b_bf16 v[238:241], v[168:169], v[80:81], v[238:241] cbsz:4 abid:10
	v_mfma_f32_4x4x4_16b_bf16 v[242:245], v[168:169], v[88:89], v[242:245] cbsz:4 abid:10
	v_fma_f32 v209, v150, v208, v209
	v_fma_f32 v213, v150, v212, v213
	v_mfma_f32_4x4x4_16b_bf16 v[198:201], v[170:171], v[66:67], v[198:201] cbsz:4 abid:13
	v_fma_f32 v209, v16, v212, v209
	v_fma_f32 v213, v17, v208, v213
	v_mfma_f32_4x4x4_16b_bf16 v[202:205], v[170:171], v[74:75], v[202:205] cbsz:4 abid:13
	v_fma_f32 v230, v152, v231, v230
	v_fma_f32 v234, v152, v235, v234
	v_mfma_f32_4x4x4_16b_bf16 v[238:241], v[168:169], v[82:83], v[238:241] cbsz:4 abid:14
	v_fma_f32 v230, v36, v235, v230
	v_fma_f32 v234, v37, v231, v234
	v_mfma_f32_4x4x4_16b_bf16 v[242:245], v[168:169], v[90:91], v[242:245] cbsz:4 abid:14
	v_cvt_pk_bf16_f32 v135, v209, v213
	v_cvt_pk_bf16_f32 v187, v230, v234
	ds_write2_b32 v193, v132, v135 offset0:136 offset1:204
	ds_write2_b32 v254, v187, v143 offset0:0 offset1:68
	v_fma_f32 v214, v150, v209, v214
	v_fma_f32 v218, v150, v213, v218
	v_fma_f32 v214, v16, v213, v214
	v_fma_f32 v218, v17, v209, v218
	v_fma_f32 v225, v152, v230, v225
	v_fma_f32 v229, v152, v234, v229
	v_fma_f32 v225, v36, v234, v225
	v_fma_f32 v229, v37, v230, v229
	v_cvt_pk_bf16_f32 v128, v214, v218
	v_cvt_pk_bf16_f32 v136, v225, v229
	v_add_u32_e32 v193, 0x34c0, v103
	v_add_u32_e32 v254, 0x3900, v103
	v_fma_f32 v215, v150, v214, v215
	v_fma_f32 v219, v150, v218, v219
	v_fma_f32 v215, v16, v218, v215
	v_fma_f32 v219, v17, v214, v219
	v_fma_f32 v224, v152, v225, v224
	v_fma_f32 v228, v152, v229, v228
	v_fma_f32 v224, v36, v229, v224
	v_fma_f32 v228, v37, v225, v228
	v_cvt_pk_bf16_f32 v131, v215, v219
	v_cvt_pk_bf16_f32 v139, v224, v228
	ds_write2_b32 v193, v128, v131 offset0:0 offset1:68
	ds_write2_b32 v254, v139, v136 offset0:136 offset1:204
	v_fma_f32 v216, v150, v215, v216
	v_fma_f32 v220, v150, v219, v220
	v_fma_f32 v216, v16, v219, v216
	v_fma_f32 v220, v17, v215, v220
	v_fma_f32 v223, v152, v224, v223
	v_fma_f32 v227, v152, v228, v227
	v_fma_f32 v223, v36, v228, v223
	v_fma_f32 v227, v37, v224, v227
	v_cvt_pk_bf16_f32 v132, v216, v220
	v_cvt_pk_bf16_f32 v143, v223, v227
	v_fma_f32 v217, v150, v216, v217
	v_fma_f32 v221, v150, v220, v221
	v_fma_f32 v217, v16, v220, v217
	v_fma_f32 v221, v17, v216, v221
	v_fma_f32 v222, v152, v223, v222
	v_fma_f32 v226, v152, v227, v226
	v_fma_f32 v222, v36, v227, v222
	v_fma_f32 v226, v37, v223, v226
	v_cvt_pk_bf16_f32 v135, v217, v221
	v_cvt_pk_bf16_f32 v187, v222, v226
	ds_write2_b32 v193, v132, v135 offset0:136 offset1:204
	ds_write2_b32 v254, v187, v143 offset0:0 offset1:68
	v_mov_b32_e32 v114, v217
	v_mov_b32_e32 v119, v221
	v_mov_b32_e32 v121, v222
	v_mov_b32_e32 v127, v226
	ds_read_b128 v[206:209], v110 offset:10240
	ds_read_b128 v[210:213], v110 offset:10304
	ds_read_b128 v[214:217], v110 offset:10368
	ds_read_b128 v[218:221], v110 offset:10432
	ds_read_b128 v[222:225], v110 offset:14592
	ds_read_b128 v[226:229], v110 offset:14656
	ds_read_b128 v[230:233], v110 offset:14720
	ds_read_b128 v[234:237], v110 offset:14784
	s_waitcnt lgkmcnt(7)
	v_mfma_f32_16x16x32_bf16 v[48:51], v[0:3], v[206:209], 0
	s_waitcnt lgkmcnt(3)
	v_mfma_f32_16x16x32_bf16 v[44:47], v[20:23], v[222:225], 0
	v_mfma_f32_16x16x32_bf16 v[48:51], v[4:7], v[210:213], v[48:51]
	s_waitcnt lgkmcnt(2)
	v_mfma_f32_16x16x32_bf16 v[44:47], v[24:27], v[226:229], v[44:47]
	v_mfma_f32_16x16x32_bf16 v[48:51], v[8:11], v[214:217], v[48:51]
	s_waitcnt lgkmcnt(1)
	v_mfma_f32_16x16x32_bf16 v[44:47], v[28:31], v[230:233], v[44:47]
	v_mfma_f32_16x16x32_bf16 v[48:51], v[12:15], v[218:221], v[48:51]
	s_waitcnt lgkmcnt(0)
; #define LAS __attribute__((address_space(3)))
; __device__ __forceinline__ unsigned pk2(float lo, float hi) { f32x2 v = {lo, hi}; nbf2 r = __builtin_convertvector(v, nbf2); return __builtin_bit_cast(unsigned, r); }
; __device__ __forceinline__ float bf_at(const u32x4& lo, const u32x4& hi, int r) { const unsigned w = (r < 8 ? lo : hi)[(r & 7) >> 1]; return (r & 1) ? bf_hi(w) : bf_lo(w); }
; __device__ __forceinline__ void s5_out_phase(LAS unsigned char* lds, const bf16_t* UZ, const unsigned char* ws, const float* dskip, bf16_t* YG) {
;     ...
; #pragma unroll
;             for (int nt = 0; nt < 8; ++nt) {
;                 const f32x4 z = {0.f, 0.f, 0.f, 0.f};
;                 const f32x4 cf = __builtin_amdgcn_mfma_f32_16x16x16bf16_1k(Uf[mf], Bf[0][nt], z, 0, 0, 0);
;                 const f32x4 cb = __builtin_amdgcn_mfma_f32_16x16x16bf16_1k(Uf[mb], Bf[1][nt], z, 0, 0, 0);
;                 u32x2 wf, wb; wf.x = pk2(cf[0], cf[1]); wf.y = pk2(cf[2], cf[3]); wb.x = pk2(cb[0], cb[1]); wb.y = pk2(cb[2], cb[3]);
;                 *(LAS u32x2*)(wl + nt * 640 + wofs) = wf;
;                 *(LAS u32x2*)(wl + BUT_BYTES + nt * 640 + wofs) = wb;
;             }
;     ...
; #pragma unroll
;             for (int rr = 0; rr < 16; ++rr) {
;                 const int r = rr, rb = 15 - rr;
;                 { const f32x2 bb = {bf_at(fre0, fre1, r), bf_at(fim0, fim1, r)};
;                   const f32x2 n2 = cmac((f32x2){xfr, xfi}, (f32x2){ap[0].x, ap[0].x}, (f32x2){-ap[0].y, ap[0].y}, bb); xfr = n2.x; xfi = n2.y;
;                   *(LAS unsigned*)(xf + r * XB_PITCH + lane * 4) = pk2(n2.x, n2.y); }
;                 { const f32x2 bb = {bf_at(bre0, bre1, rb), bf_at(bim0, bim1, rb)};
;                   const f32x2 n2 = cmac((f32x2){xbr, xbi}, (f32x2){ap[1].x, ap[1].x}, (f32x2){-ap[1].y, ap[1].y}, bb); xbr = n2.x; xbi = n2.y;
;                   *(LAS unsigned*)(xbk + rb * XB_PITCH + lane * 4) = pk2(n2.x, n2.y); }
;             }
	v_mfma_f32_16x16x32_bf16 v[44:47], v[32:35], v[234:237], v[44:47]
	v_mfma_f32_4x4x4_16b_bf16 v[206:209], v[170:171], v[60:61], 0 cbsz:4 abid:2
	v_mfma_f32_4x4x4_16b_bf16 v[210:213], v[170:171], v[68:69], 0 cbsz:4 abid:2
	v_mfma_f32_4x4x4_16b_bf16 v[214:217], v[170:171], v[60:61], 0 cbsz:4 abid:3
	v_mfma_f32_4x4x4_16b_bf16 v[218:221], v[170:171], v[68:69], 0 cbsz:4 abid:3
	v_mfma_f32_4x4x4_16b_bf16 v[222:225], v[168:169], v[76:77], 0 cbsz:4 abid:0
	v_mfma_f32_4x4x4_16b_bf16 v[226:229], v[168:169], v[84:85], 0 cbsz:4 abid:0
	v_mfma_f32_4x4x4_16b_bf16 v[230:233], v[168:169], v[76:77], 0 cbsz:4 abid:1
	v_mfma_f32_4x4x4_16b_bf16 v[234:237], v[168:169], v[84:85], 0 cbsz:4 abid:1
	v_mfma_f32_4x4x4_16b_bf16 v[206:209], v[170:171], v[62:63], v[206:209] cbsz:4 abid:6
	v_mfma_f32_4x4x4_16b_bf16 v[210:213], v[170:171], v[70:71], v[210:213] cbsz:4 abid:6
	v_mfma_f32_4x4x4_16b_bf16 v[214:217], v[170:171], v[62:63], v[214:217] cbsz:4 abid:7
	v_mfma_f32_4x4x4_16b_bf16 v[218:221], v[170:171], v[70:71], v[218:221] cbsz:4 abid:7
	v_mfma_f32_4x4x4_16b_bf16 v[222:225], v[168:169], v[78:79], v[222:225] cbsz:4 abid:4
	v_mfma_f32_4x4x4_16b_bf16 v[226:229], v[168:169], v[86:87], v[226:229] cbsz:4 abid:4
	v_mfma_f32_4x4x4_16b_bf16 v[230:233], v[168:169], v[78:79], v[230:233] cbsz:4 abid:5
	v_mfma_f32_4x4x4_16b_bf16 v[234:237], v[168:169], v[86:87], v[234:237] cbsz:4 abid:5
	v_mfma_f32_4x4x4_16b_bf16 v[206:209], v[170:171], v[64:65], v[206:209] cbsz:4 abid:10
	v_mfma_f32_4x4x4_16b_bf16 v[210:213], v[170:171], v[72:73], v[210:213] cbsz:4 abid:10
	v_mfma_f32_4x4x4_16b_bf16 v[214:217], v[170:171], v[64:65], v[214:217] cbsz:4 abid:11
	v_mfma_f32_4x4x4_16b_bf16 v[218:221], v[170:171], v[72:73], v[218:221] cbsz:4 abid:11
	v_mfma_f32_4x4x4_16b_bf16 v[222:225], v[168:169], v[80:81], v[222:225] cbsz:4 abid:8
	v_mfma_f32_4x4x4_16b_bf16 v[226:229], v[168:169], v[88:89], v[226:229] cbsz:4 abid:8
	v_mfma_f32_4x4x4_16b_bf16 v[230:233], v[168:169], v[80:81], v[230:233] cbsz:4 abid:9
	v_mfma_f32_4x4x4_16b_bf16 v[234:237], v[168:169], v[88:89], v[234:237] cbsz:4 abid:9
	v_mfma_f32_4x4x4_16b_bf16 v[206:209], v[170:171], v[66:67], v[206:209] cbsz:4 abid:14
	v_mfma_f32_4x4x4_16b_bf16 v[210:213], v[170:171], v[74:75], v[210:213] cbsz:4 abid:14
	v_mfma_f32_4x4x4_16b_bf16 v[214:217], v[170:171], v[66:67], v[214:217] cbsz:4 abid:15
	v_mfma_f32_4x4x4_16b_bf16 v[218:221], v[170:171], v[74:75], v[218:221] cbsz:4 abid:15
	v_mfma_f32_4x4x4_16b_bf16 v[222:225], v[168:169], v[82:83], v[222:225] cbsz:4 abid:12
	v_mfma_f32_4x4x4_16b_bf16 v[226:229], v[168:169], v[90:91], v[226:229] cbsz:4 abid:12
	v_mfma_f32_4x4x4_16b_bf16 v[230:233], v[168:169], v[82:83], v[230:233] cbsz:4 abid:13
	v_mfma_f32_4x4x4_16b_bf16 v[234:237], v[168:169], v[90:91], v[234:237] cbsz:4 abid:13
	v_fma_f32 v188, v150, v114, v188
	v_fma_f32 v194, v150, v119, v194
	v_fma_f32 v188, v16, v119, v188
	v_fma_f32 v194, v17, v114, v194
	v_fma_f32 v249, v152, v121, v249
	v_fma_f32 v253, v152, v127, v253
	v_fma_f32 v249, v36, v127, v249
	v_fma_f32 v253, v37, v121, v253
	v_cvt_pk_bf16_f32 v128, v188, v194
	v_cvt_pk_bf16_f32 v136, v249, v253
	v_add_u32_e32 v193, 0x2800, v103
	v_add_u32_e32 v254, 0x45c0, v103
	v_fma_f32 v189, v150, v188, v189
	v_fma_f32 v195, v150, v194, v195
	v_fma_f32 v189, v16, v194, v189
	v_fma_f32 v195, v17, v188, v195
	v_fma_f32 v248, v152, v249, v248
	v_fma_f32 v252, v152, v253, v252
	v_fma_f32 v248, v36, v253, v248
	v_fma_f32 v252, v37, v249, v252
	v_cvt_pk_bf16_f32 v131, v189, v195
	v_cvt_pk_bf16_f32 v139, v248, v252
	ds_write2_b32 v193, v128, v131 offset0:0 offset1:68
	ds_write2_b32 v254, v139, v136 offset0:136 offset1:204
	v_fma_f32 v190, v150, v189, v190
	v_fma_f32 v196, v150, v195, v196
	v_fma_f32 v190, v16, v195, v190
	v_fma_f32 v196, v17, v189, v196
	v_fma_f32 v247, v152, v248, v247
	v_fma_f32 v251, v152, v252, v251
	v_fma_f32 v247, v36, v252, v247
	v_fma_f32 v251, v37, v248, v251
	v_cvt_pk_bf16_f32 v132, v190, v196
	v_cvt_pk_bf16_f32 v143, v247, v251
	v_fma_f32 v191, v150, v190, v191
	v_fma_f32 v197, v150, v196, v197
	v_fma_f32 v191, v16, v196, v191
	v_fma_f32 v197, v17, v190, v197
	v_fma_f32 v246, v152, v247, v246
	v_fma_f32 v250, v152, v251, v250
	v_fma_f32 v246, v36, v251, v246
	v_fma_f32 v250, v37, v247, v250
	v_cvt_pk_bf16_f32 v135, v191, v197
	v_cvt_pk_bf16_f32 v187, v246, v250
	ds_write2_b32 v193, v132, v135 offset0:136 offset1:204
	ds_write2_b32 v254, v187, v143 offset0:0 offset1:68
	v_fma_f32 v198, v150, v191, v198
	v_fma_f32 v202, v150, v197, v202
	v_fma_f32 v198, v16, v197, v198
	v_fma_f32 v202, v17, v191, v202
	v_fma_f32 v241, v152, v246, v241
	v_fma_f32 v245, v152, v250, v245
	v_fma_f32 v241, v36, v250, v241
	v_fma_f32 v245, v37, v246, v245
	v_cvt_pk_bf16_f32 v128, v198, v202
	v_cvt_pk_bf16_f32 v136, v241, v245
	v_add_u32_e32 v193, 0x2c40, v103
	v_add_u32_e32 v254, 0x4180, v103
	v_fma_f32 v199, v150, v198, v199
	v_fma_f32 v203, v150, v202, v203
	v_mfma_f32_4x4x4_16b_bf16 v[188:191], v[168:169], v[60:61], 0 cbsz:4 abid:0
	v_fma_f32 v199, v16, v202, v199
	v_fma_f32 v203, v17, v198, v203
	v_mfma_f32_4x4x4_16b_bf16 v[194:197], v[168:169], v[68:69], 0 cbsz:4 abid:0
	v_fma_f32 v240, v152, v241, v240
	v_fma_f32 v244, v152, v245, v244
	v_mfma_f32_4x4x4_16b_bf16 v[246:249], v[170:171], v[76:77], 0 cbsz:4 abid:3
	v_fma_f32 v240, v36, v245, v240
	v_fma_f32 v244, v37, v241, v244
	v_mfma_f32_4x4x4_16b_bf16 v[250:253], v[170:171], v[84:85], 0 cbsz:4 abid:3
	v_cvt_pk_bf16_f32 v131, v199, v203
	v_cvt_pk_bf16_f32 v139, v240, v244
	ds_write2_b32 v193, v128, v131 offset0:0 offset1:68
	ds_write2_b32 v254, v139, v136 offset0:136 offset1:204
	v_mfma_f32_4x4x4_16b_bf16 v[188:191], v[168:169], v[62:63], v[188:191] cbsz:4 abid:4
; #define LAS __attribute__((address_space(3)))
; __device__ __forceinline__ unsigned pk2(float lo, float hi) { f32x2 v = {lo, hi}; nbf2 r = __builtin_convertvector(v, nbf2); return __builtin_bit_cast(unsigned, r); }
; #define WAVE_LDS_FENCE() asm volatile("s_waitcnt lgkmcnt(0)" ::: "memory")
; __device__ __forceinline__ float bf_at(const u32x4& lo, const u32x4& hi, int r) { const unsigned w = (r < 8 ? lo : hi)[(r & 7) >> 1]; return (r & 1) ? bf_hi(w) : bf_lo(w); }
; __device__ __forceinline__ void s5_out_phase(LAS unsigned char* lds, const bf16_t* UZ, const unsigned char* ws, const float* dskip, bf16_t* YG) {
;     ...
; #pragma unroll
;             for (int rr = 0; rr < 16; ++rr) {
;                 const int r = rr, rb = 15 - rr;
;                 { const f32x2 bb = {bf_at(fre0, fre1, r), bf_at(fim0, fim1, r)};
;                   const f32x2 n2 = cmac((f32x2){xfr, xfi}, (f32x2){ap[0].x, ap[0].x}, (f32x2){-ap[0].y, ap[0].y}, bb); xfr = n2.x; xfi = n2.y;
;                   *(LAS unsigned*)(xf + r * XB_PITCH + lane * 4) = pk2(n2.x, n2.y); }
;                 { const f32x2 bb = {bf_at(bre0, bre1, rb), bf_at(bim0, bim1, rb)};
;                   const f32x2 n2 = cmac((f32x2){xbr, xbi}, (f32x2){ap[1].x, ap[1].x}, (f32x2){-ap[1].y, ap[1].y}, bb); xbr = n2.x; xbi = n2.y;
;                   *(LAS unsigned*)(xbk + rb * XB_PITCH + lane * 4) = pk2(n2.x, n2.y); }
;             }
;             WAVE_LDS_FENCE();
; #pragma unroll
;             for (int ks = 0; ks < 4; ++ks) {
;                 const bf16x8 Xf = *(const LAS bf16x8*)(xf + fr * XB_PITCH + (8 * fq + 32 * ks) * 2);
;                 const bf16x8 Xb = *(const LAS bf16x8*)(xbk + fr * XB_PITCH + (8 * fq + 32 * ks) * 2);
	v_mfma_f32_4x4x4_16b_bf16 v[194:197], v[168:169], v[70:71], v[194:197] cbsz:4 abid:4
	v_fma_f32 v200, v150, v199, v200
	v_fma_f32 v204, v150, v203, v204
	v_mfma_f32_4x4x4_16b_bf16 v[246:249], v[170:171], v[78:79], v[246:249] cbsz:4 abid:7
	v_fma_f32 v200, v16, v203, v200
	v_fma_f32 v204, v17, v199, v204
	v_mfma_f32_4x4x4_16b_bf16 v[250:253], v[170:171], v[86:87], v[250:253] cbsz:4 abid:7
	v_fma_f32 v239, v152, v240, v239
	v_fma_f32 v243, v152, v244, v243
	v_mfma_f32_4x4x4_16b_bf16 v[188:191], v[168:169], v[64:65], v[188:191] cbsz:4 abid:8
	v_fma_f32 v239, v36, v244, v239
	v_fma_f32 v243, v37, v240, v243
	v_mfma_f32_4x4x4_16b_bf16 v[194:197], v[168:169], v[72:73], v[194:197] cbsz:4 abid:8
	v_cvt_pk_bf16_f32 v132, v200, v204
	v_cvt_pk_bf16_f32 v143, v239, v243
	v_mfma_f32_4x4x4_16b_bf16 v[246:249], v[170:171], v[80:81], v[246:249] cbsz:4 abid:11
	v_mfma_f32_4x4x4_16b_bf16 v[250:253], v[170:171], v[88:89], v[250:253] cbsz:4 abid:11
	v_fma_f32 v201, v150, v200, v201
	v_fma_f32 v205, v150, v204, v205
	v_mfma_f32_4x4x4_16b_bf16 v[188:191], v[168:169], v[66:67], v[188:191] cbsz:4 abid:12
	v_fma_f32 v201, v16, v204, v201
	v_fma_f32 v205, v17, v200, v205
	v_mfma_f32_4x4x4_16b_bf16 v[194:197], v[168:169], v[74:75], v[194:197] cbsz:4 abid:12
	v_fma_f32 v238, v152, v239, v238
	v_fma_f32 v242, v152, v243, v242
	v_mfma_f32_4x4x4_16b_bf16 v[246:249], v[170:171], v[82:83], v[246:249] cbsz:4 abid:15
	v_fma_f32 v238, v36, v243, v238
	v_fma_f32 v242, v37, v239, v242
	v_mfma_f32_4x4x4_16b_bf16 v[250:253], v[170:171], v[90:91], v[250:253] cbsz:4 abid:15
	v_cvt_pk_bf16_f32 v135, v201, v205
	v_cvt_pk_bf16_f32 v187, v238, v242
	ds_write2_b32 v193, v132, v135 offset0:136 offset1:204
	ds_write2_b32 v254, v187, v143 offset0:0 offset1:68
	v_fma_f32 v206, v150, v201, v206
	v_fma_f32 v210, v150, v205, v210
	v_fma_f32 v206, v16, v205, v206
	v_fma_f32 v210, v17, v201, v210
	v_fma_f32 v233, v152, v238, v233
	v_fma_f32 v237, v152, v242, v237
	v_fma_f32 v233, v36, v242, v233
	v_fma_f32 v237, v37, v238, v237
	v_cvt_pk_bf16_f32 v128, v206, v210
	v_cvt_pk_bf16_f32 v136, v233, v237
	v_add_u32_e32 v193, 0x3080, v103
	v_add_u32_e32 v254, 0x3d40, v103
	v_fma_f32 v207, v150, v206, v207
	v_fma_f32 v211, v150, v210, v211
	v_mfma_f32_4x4x4_16b_bf16 v[198:201], v[168:169], v[60:61], 0 cbsz:4 abid:1
	v_fma_f32 v207, v16, v210, v207
	v_fma_f32 v211, v17, v206, v211
	v_mfma_f32_4x4x4_16b_bf16 v[202:205], v[168:169], v[68:69], 0 cbsz:4 abid:1
	v_fma_f32 v232, v152, v233, v232
	v_fma_f32 v236, v152, v237, v236
	v_mfma_f32_4x4x4_16b_bf16 v[238:241], v[170:171], v[76:77], 0 cbsz:4 abid:2
	v_fma_f32 v232, v36, v237, v232
	v_fma_f32 v236, v37, v233, v236
	v_mfma_f32_4x4x4_16b_bf16 v[242:245], v[170:171], v[84:85], 0 cbsz:4 abid:2
	v_cvt_pk_bf16_f32 v131, v207, v211
	v_cvt_pk_bf16_f32 v139, v232, v236
	ds_write2_b32 v193, v128, v131 offset0:0 offset1:68
	ds_write2_b32 v254, v139, v136 offset0:136 offset1:204
	v_mfma_f32_4x4x4_16b_bf16 v[198:201], v[168:169], v[62:63], v[198:201] cbsz:4 abid:5
	v_mfma_f32_4x4x4_16b_bf16 v[202:205], v[168:169], v[70:71], v[202:205] cbsz:4 abid:5
	v_fma_f32 v208, v150, v207, v208
	v_fma_f32 v212, v150, v211, v212
	v_mfma_f32_4x4x4_16b_bf16 v[238:241], v[170:171], v[78:79], v[238:241] cbsz:4 abid:6
	v_fma_f32 v208, v16, v211, v208
	v_fma_f32 v212, v17, v207, v212
	v_mfma_f32_4x4x4_16b_bf16 v[242:245], v[170:171], v[86:87], v[242:245] cbsz:4 abid:6
	v_fma_f32 v231, v152, v232, v231
	v_fma_f32 v235, v152, v236, v235
	v_mfma_f32_4x4x4_16b_bf16 v[198:201], v[168:169], v[64:65], v[198:201] cbsz:4 abid:9
	v_fma_f32 v231, v36, v236, v231
	v_fma_f32 v235, v37, v232, v235
	v_mfma_f32_4x4x4_16b_bf16 v[202:205], v[168:169], v[72:73], v[202:205] cbsz:4 abid:9
	v_cvt_pk_bf16_f32 v132, v208, v212
	v_cvt_pk_bf16_f32 v143, v231, v235
	v_mfma_f32_4x4x4_16b_bf16 v[238:241], v[170:171], v[80:81], v[238:241] cbsz:4 abid:10
	v_mfma_f32_4x4x4_16b_bf16 v[242:245], v[170:171], v[88:89], v[242:245] cbsz:4 abid:10
	v_fma_f32 v209, v150, v208, v209
	v_fma_f32 v213, v150, v212, v213
	v_mfma_f32_4x4x4_16b_bf16 v[198:201], v[168:169], v[66:67], v[198:201] cbsz:4 abid:13
	v_fma_f32 v209, v16, v212, v209
	v_fma_f32 v213, v17, v208, v213
	v_mfma_f32_4x4x4_16b_bf16 v[202:205], v[168:169], v[74:75], v[202:205] cbsz:4 abid:13
	v_fma_f32 v230, v152, v231, v230
	v_fma_f32 v234, v152, v235, v234
	v_mfma_f32_4x4x4_16b_bf16 v[238:241], v[170:171], v[82:83], v[238:241] cbsz:4 abid:14
	v_fma_f32 v230, v36, v235, v230
	v_fma_f32 v234, v37, v231, v234
	v_mfma_f32_4x4x4_16b_bf16 v[242:245], v[170:171], v[90:91], v[242:245] cbsz:4 abid:14
	v_cvt_pk_bf16_f32 v135, v209, v213
	v_cvt_pk_bf16_f32 v187, v230, v234
	ds_write2_b32 v193, v132, v135 offset0:136 offset1:204
	ds_write2_b32 v254, v187, v143 offset0:0 offset1:68
	v_fma_f32 v214, v150, v209, v214
	v_fma_f32 v218, v150, v213, v218
	v_fma_f32 v214, v16, v213, v214
	v_fma_f32 v218, v17, v209, v218
	v_fma_f32 v225, v152, v230, v225
	v_fma_f32 v229, v152, v234, v229
	v_fma_f32 v225, v36, v234, v225
	v_fma_f32 v229, v37, v230, v229
	v_cvt_pk_bf16_f32 v128, v214, v218
	v_cvt_pk_bf16_f32 v136, v225, v229
	v_add_u32_e32 v193, 0x34c0, v103
	v_add_u32_e32 v254, 0x3900, v103
	v_fma_f32 v215, v150, v214, v215
	v_fma_f32 v219, v150, v218, v219
	v_fma_f32 v215, v16, v218, v215
	v_fma_f32 v219, v17, v214, v219
	v_fma_f32 v224, v152, v225, v224
	v_fma_f32 v228, v152, v229, v228
	v_fma_f32 v224, v36, v229, v224
	v_fma_f32 v228, v37, v225, v228
	v_cvt_pk_bf16_f32 v131, v215, v219
	v_cvt_pk_bf16_f32 v139, v224, v228
	ds_write2_b32 v193, v128, v131 offset0:0 offset1:68
	ds_write2_b32 v254, v139, v136 offset0:136 offset1:204
	v_fma_f32 v216, v150, v215, v216
	v_fma_f32 v220, v150, v219, v220
	v_fma_f32 v216, v16, v219, v216
	v_fma_f32 v220, v17, v215, v220
	v_fma_f32 v223, v152, v224, v223
	v_fma_f32 v227, v152, v228, v227
	v_fma_f32 v223, v36, v228, v223
	v_fma_f32 v227, v37, v224, v227
	v_cvt_pk_bf16_f32 v132, v216, v220
	v_cvt_pk_bf16_f32 v143, v223, v227
	v_fma_f32 v217, v150, v216, v217
	v_fma_f32 v221, v150, v220, v221
	v_fma_f32 v217, v16, v220, v217
	v_fma_f32 v221, v17, v216, v221
	v_fma_f32 v222, v152, v223, v222
	v_fma_f32 v226, v152, v227, v226
	v_fma_f32 v222, v36, v227, v222
	v_fma_f32 v226, v37, v223, v226
	v_cvt_pk_bf16_f32 v135, v217, v221
	v_cvt_pk_bf16_f32 v187, v222, v226
	ds_write2_b32 v193, v132, v135 offset0:136 offset1:204
	ds_write2_b32 v254, v187, v143 offset0:0 offset1:68
	v_mov_b32_e32 v114, v217
	v_mov_b32_e32 v119, v221
	v_mov_b32_e32 v121, v222
	v_mov_b32_e32 v127, v226
	ds_read_b128 v[206:209], v110 offset:10240
	ds_read_b128 v[210:213], v110 offset:10304
	ds_read_b128 v[214:217], v110 offset:10368
	ds_read_b128 v[218:221], v110 offset:10432
	ds_read_b128 v[222:225], v110 offset:14592
	ds_read_b128 v[226:229], v110 offset:14656
	ds_read_b128 v[230:233], v110 offset:14720
	ds_read_b128 v[234:237], v110 offset:14784
	s_waitcnt lgkmcnt(7)
; #define LAS __attribute__((address_space(3)))
; __device__ __forceinline__ void s5_out_phase(LAS unsigned char* lds, const bf16_t* UZ, const unsigned char* ws, const float* dskip, bf16_t* YG) {
;     ...
; #pragma unroll
;             for (int nt = 0; nt < 8; ++nt) {
;                 const f32x4 z = {0.f, 0.f, 0.f, 0.f};
;                 const f32x4 cf = __builtin_amdgcn_mfma_f32_16x16x16bf16_1k(Uf[mf], Bf[0][nt], z, 0, 0, 0);
;                 const f32x4 cb = __builtin_amdgcn_mfma_f32_16x16x16bf16_1k(Uf[mb], Bf[1][nt], z, 0, 0, 0);
;                 u32x2 wf, wb; wf.x = pk2(cf[0], cf[1]); wf.y = pk2(cf[2], cf[3]); wb.x = pk2(cb[0], cb[1]); wb.y = pk2(cb[2], cb[3]);
;                 *(LAS u32x2*)(wl + nt * 640 + wofs) = wf;
;                 *(LAS u32x2*)(wl + BUT_BYTES + nt * 640 + wofs) = wb;
;             }
;             WAVE_LDS_FENCE();
;             const LAS unsigned char* rp = wl + lane * 80;
;             const u32x4 fre0 = *(const LAS u32x4*)(rp), fre1 = *(const LAS u32x4*)(rp + 16), fim0 = *(const LAS u32x4*)(rp + 32), fim1 = *(const LAS u32x4*)(rp + 48);
;             const u32x4 bre0 = *(const LAS u32x4*)(rp + BUT_BYTES), bre1 = *(const LAS u32x4*)(rp + BUT_BYTES + 16), bim0 = *(const LAS u32x4*)(rp + BUT_BYTES + 32), bim1 = *(const LAS u32x4*)(rp + BUT_BYTES + 48);
;             LAS unsigned char* xf = wl + 2 * BUT_BYTES; LAS unsigned char* xbk = xf + XB_BYTES;
; #pragma unroll
;             for (int rr = 0; rr < 16; ++rr) {
;                 const int r = rr, rb = 15 - rr;
;                 { const f32x2 bb = {bf_at(fre0, fre1, r), bf_at(fim0, fim1, r)};
;                   const f32x2 n2 = cmac((f32x2){xfr, xfi}, (f32x2){ap[0].x, ap[0].x}, (f32x2){-ap[0].y, ap[0].y}, bb); xfr = n2.x; xfi = n2.y;
;                   *(LAS unsigned*)(xf + r * XB_PITCH + lane * 4) = pk2(n2.x, n2.y); }
;                 { const f32x2 bb = {bf_at(bre0, bre1, rb), bf_at(bim0, bim1, rb)};
;                   const f32x2 n2 = cmac((f32x2){xbr, xbi}, (f32x2){ap[1].x, ap[1].x}, (f32x2){-ap[1].y, ap[1].y}, bb); xbr = n2.x; xbi = n2.y;
;                   *(LAS unsigned*)(xbk + rb * XB_PITCH + lane * 4) = pk2(n2.x, n2.y); }
;             }
;             WAVE_LDS_FENCE();
; #pragma unroll
;             for (int ks = 0; ks < 4; ++ks) {
;                 const bf16x8 Xf = *(const LAS bf16x8*)(xf + fr * XB_PITCH + (8 * fq + 32 * ks) * 2);
	v_mfma_f32_16x16x32_bf16 v[56:59], v[0:3], v[206:209], 0
	s_waitcnt lgkmcnt(3)
	v_mfma_f32_16x16x32_bf16 v[52:55], v[20:23], v[222:225], 0
	v_mfma_f32_16x16x32_bf16 v[56:59], v[4:7], v[210:213], v[56:59]
	s_waitcnt lgkmcnt(2)
	v_mfma_f32_16x16x32_bf16 v[52:55], v[24:27], v[226:229], v[52:55]
	v_mfma_f32_16x16x32_bf16 v[56:59], v[8:11], v[214:217], v[56:59]
	s_waitcnt lgkmcnt(1)
	v_mfma_f32_16x16x32_bf16 v[52:55], v[28:31], v[230:233], v[52:55]
	v_mfma_f32_16x16x32_bf16 v[56:59], v[12:15], v[218:221], v[56:59]
	s_waitcnt lgkmcnt(0)
	v_mfma_f32_16x16x32_bf16 v[52:55], v[32:35], v[234:237], v[52:55]
	v_mfma_f32_4x4x4_16b_bf16 v[206:209], v[168:169], v[60:61], 0 cbsz:4 abid:2
	v_mfma_f32_4x4x4_16b_bf16 v[210:213], v[168:169], v[68:69], 0 cbsz:4 abid:2
	v_mfma_f32_4x4x4_16b_bf16 v[214:217], v[168:169], v[60:61], 0 cbsz:4 abid:3
	v_mfma_f32_4x4x4_16b_bf16 v[218:221], v[168:169], v[68:69], 0 cbsz:4 abid:3
	v_mfma_f32_4x4x4_16b_bf16 v[222:225], v[170:171], v[76:77], 0 cbsz:4 abid:0
	v_mfma_f32_4x4x4_16b_bf16 v[226:229], v[170:171], v[84:85], 0 cbsz:4 abid:0
	v_mfma_f32_4x4x4_16b_bf16 v[230:233], v[170:171], v[76:77], 0 cbsz:4 abid:1
	v_mfma_f32_4x4x4_16b_bf16 v[234:237], v[170:171], v[84:85], 0 cbsz:4 abid:1
	v_mfma_f32_4x4x4_16b_bf16 v[206:209], v[168:169], v[62:63], v[206:209] cbsz:4 abid:6
	v_mfma_f32_4x4x4_16b_bf16 v[210:213], v[168:169], v[70:71], v[210:213] cbsz:4 abid:6
	v_mfma_f32_4x4x4_16b_bf16 v[214:217], v[168:169], v[62:63], v[214:217] cbsz:4 abid:7
	v_mfma_f32_4x4x4_16b_bf16 v[218:221], v[168:169], v[70:71], v[218:221] cbsz:4 abid:7
	v_mfma_f32_4x4x4_16b_bf16 v[222:225], v[170:171], v[78:79], v[222:225] cbsz:4 abid:4
	v_mfma_f32_4x4x4_16b_bf16 v[226:229], v[170:171], v[86:87], v[226:229] cbsz:4 abid:4
	v_mfma_f32_4x4x4_16b_bf16 v[230:233], v[170:171], v[78:79], v[230:233] cbsz:4 abid:5
	v_mfma_f32_4x4x4_16b_bf16 v[234:237], v[170:171], v[86:87], v[234:237] cbsz:4 abid:5
	v_mfma_f32_4x4x4_16b_bf16 v[206:209], v[168:169], v[64:65], v[206:209] cbsz:4 abid:10
	v_mfma_f32_4x4x4_16b_bf16 v[210:213], v[168:169], v[72:73], v[210:213] cbsz:4 abid:10
	v_mfma_f32_4x4x4_16b_bf16 v[214:217], v[168:169], v[64:65], v[214:217] cbsz:4 abid:11
	v_mfma_f32_4x4x4_16b_bf16 v[218:221], v[168:169], v[72:73], v[218:221] cbsz:4 abid:11
	v_mfma_f32_4x4x4_16b_bf16 v[222:225], v[170:171], v[80:81], v[222:225] cbsz:4 abid:8
	v_mfma_f32_4x4x4_16b_bf16 v[226:229], v[170:171], v[88:89], v[226:229] cbsz:4 abid:8
	v_mfma_f32_4x4x4_16b_bf16 v[230:233], v[170:171], v[80:81], v[230:233] cbsz:4 abid:9
	v_mfma_f32_4x4x4_16b_bf16 v[234:237], v[170:171], v[88:89], v[234:237] cbsz:4 abid:9
	v_mfma_f32_4x4x4_16b_bf16 v[206:209], v[168:169], v[66:67], v[206:209] cbsz:4 abid:14
	v_mfma_f32_4x4x4_16b_bf16 v[210:213], v[168:169], v[74:75], v[210:213] cbsz:4 abid:14
	v_mfma_f32_4x4x4_16b_bf16 v[214:217], v[168:169], v[66:67], v[214:217] cbsz:4 abid:15
	v_mfma_f32_4x4x4_16b_bf16 v[218:221], v[168:169], v[74:75], v[218:221] cbsz:4 abid:15
	v_mfma_f32_4x4x4_16b_bf16 v[222:225], v[170:171], v[82:83], v[222:225] cbsz:4 abid:12
	v_mfma_f32_4x4x4_16b_bf16 v[226:229], v[170:171], v[90:91], v[226:229] cbsz:4 abid:12
	v_mfma_f32_4x4x4_16b_bf16 v[230:233], v[170:171], v[82:83], v[230:233] cbsz:4 abid:13
	v_mfma_f32_4x4x4_16b_bf16 v[234:237], v[170:171], v[90:91], v[234:237] cbsz:4 abid:13
	v_fma_f32 v188, v150, v114, v188
	v_fma_f32 v194, v150, v119, v194
	v_fma_f32 v188, v16, v119, v188
	v_fma_f32 v194, v17, v114, v194
	v_fma_f32 v249, v152, v121, v249
	v_fma_f32 v253, v152, v127, v253
	v_fma_f32 v249, v36, v127, v249
	v_fma_f32 v253, v37, v121, v253
	v_cvt_pk_bf16_f32 v128, v188, v194
	v_cvt_pk_bf16_f32 v136, v249, v253
	v_add_u32_e32 v193, 0x2800, v103
	v_add_u32_e32 v254, 0x45c0, v103
	v_fma_f32 v189, v150, v188, v189
	v_fma_f32 v195, v150, v194, v195
	v_fma_f32 v189, v16, v194, v189
	v_fma_f32 v195, v17, v188, v195
	v_fma_f32 v248, v152, v249, v248
	v_fma_f32 v252, v152, v253, v252
	v_fma_f32 v248, v36, v253, v248
	v_fma_f32 v252, v37, v249, v252
	v_cvt_pk_bf16_f32 v131, v189, v195
	v_cvt_pk_bf16_f32 v139, v248, v252
	ds_write2_b32 v193, v128, v131 offset0:0 offset1:68
	ds_write2_b32 v254, v139, v136 offset0:136 offset1:204
	v_fma_f32 v190, v150, v189, v190
	v_fma_f32 v196, v150, v195, v196
	v_fma_f32 v190, v16, v195, v190
	v_fma_f32 v196, v17, v189, v196
	v_fma_f32 v247, v152, v248, v247
	v_fma_f32 v251, v152, v252, v251
	v_fma_f32 v247, v36, v252, v247
	v_fma_f32 v251, v37, v248, v251
	v_cvt_pk_bf16_f32 v132, v190, v196
	v_cvt_pk_bf16_f32 v143, v247, v251
	v_fma_f32 v191, v150, v190, v191
	v_fma_f32 v197, v150, v196, v197
	v_fma_f32 v191, v16, v196, v191
	v_fma_f32 v197, v17, v190, v197
	v_fma_f32 v246, v152, v247, v246
	v_fma_f32 v250, v152, v251, v250
	v_fma_f32 v246, v36, v251, v246
	v_fma_f32 v250, v37, v247, v250
	v_cvt_pk_bf16_f32 v135, v191, v197
	v_cvt_pk_bf16_f32 v187, v246, v250
	ds_write2_b32 v193, v132, v135 offset0:136 offset1:204
	ds_write2_b32 v254, v187, v143 offset0:0 offset1:68
	v_fma_f32 v198, v150, v191, v198
	v_fma_f32 v202, v150, v197, v202
	v_fma_f32 v198, v16, v197, v198
	v_fma_f32 v202, v17, v191, v202
	v_fma_f32 v241, v152, v246, v241
	v_fma_f32 v245, v152, v250, v245
	v_fma_f32 v241, v36, v250, v241
	v_fma_f32 v245, v37, v246, v245
	v_cvt_pk_bf16_f32 v128, v198, v202
	v_cvt_pk_bf16_f32 v136, v241, v245
	v_add_u32_e32 v193, 0x2c40, v103
	v_add_u32_e32 v254, 0x4180, v103
	v_fma_f32 v199, v150, v198, v199
	v_fma_f32 v203, v150, v202, v203
	v_mfma_f32_4x4x4_16b_bf16 v[188:191], v[116:117], v[60:61], 0 cbsz:4 abid:0
	v_fma_f32 v199, v16, v202, v199
	v_fma_f32 v203, v17, v198, v203
	v_mfma_f32_4x4x4_16b_bf16 v[194:197], v[116:117], v[68:69], 0 cbsz:4 abid:0
; #define LAS __attribute__((address_space(3)))
; __device__ __forceinline__ unsigned pk2(float lo, float hi) { f32x2 v = {lo, hi}; nbf2 r = __builtin_convertvector(v, nbf2); return __builtin_bit_cast(unsigned, r); }
; __device__ __forceinline__ float bf_at(const u32x4& lo, const u32x4& hi, int r) { const unsigned w = (r < 8 ? lo : hi)[(r & 7) >> 1]; return (r & 1) ? bf_hi(w) : bf_lo(w); }
; __device__ __forceinline__ void s5_out_phase(LAS unsigned char* lds, const bf16_t* UZ, const unsigned char* ws, const float* dskip, bf16_t* YG) {
;     ...
; #pragma unroll
;             for (int nt = 0; nt < 8; ++nt) {
;                 const f32x4 z = {0.f, 0.f, 0.f, 0.f};
;                 const f32x4 cf = __builtin_amdgcn_mfma_f32_16x16x16bf16_1k(Uf[mf], Bf[0][nt], z, 0, 0, 0);
;                 const f32x4 cb = __builtin_amdgcn_mfma_f32_16x16x16bf16_1k(Uf[mb], Bf[1][nt], z, 0, 0, 0);
;                 u32x2 wf, wb; wf.x = pk2(cf[0], cf[1]); wf.y = pk2(cf[2], cf[3]); wb.x = pk2(cb[0], cb[1]); wb.y = pk2(cb[2], cb[3]);
;                 *(LAS u32x2*)(wl + nt * 640 + wofs) = wf;
;                 *(LAS u32x2*)(wl + BUT_BYTES + nt * 640 + wofs) = wb;
;             }
;     ...
; #pragma unroll
;             for (int rr = 0; rr < 16; ++rr) {
;                 const int r = rr, rb = 15 - rr;
;                 { const f32x2 bb = {bf_at(fre0, fre1, r), bf_at(fim0, fim1, r)};
;                   const f32x2 n2 = cmac((f32x2){xfr, xfi}, (f32x2){ap[0].x, ap[0].x}, (f32x2){-ap[0].y, ap[0].y}, bb); xfr = n2.x; xfi = n2.y;
;                   *(LAS unsigned*)(xf + r * XB_PITCH + lane * 4) = pk2(n2.x, n2.y); }
;                 { const f32x2 bb = {bf_at(bre0, bre1, rb), bf_at(bim0, bim1, rb)};
;                   const f32x2 n2 = cmac((f32x2){xbr, xbi}, (f32x2){ap[1].x, ap[1].x}, (f32x2){-ap[1].y, ap[1].y}, bb); xbr = n2.x; xbi = n2.y;
;                   *(LAS unsigned*)(xbk + rb * XB_PITCH + lane * 4) = pk2(n2.x, n2.y); }
;             }
	v_fma_f32 v240, v152, v241, v240
	v_fma_f32 v244, v152, v245, v244
	v_mfma_f32_4x4x4_16b_bf16 v[246:249], v[172:173], v[76:77], 0 cbsz:4 abid:3
	v_fma_f32 v240, v36, v245, v240
	v_fma_f32 v244, v37, v241, v244
	v_mfma_f32_4x4x4_16b_bf16 v[250:253], v[172:173], v[84:85], 0 cbsz:4 abid:3
	v_cvt_pk_bf16_f32 v131, v199, v203
	v_cvt_pk_bf16_f32 v139, v240, v244
	ds_write2_b32 v193, v128, v131 offset0:0 offset1:68
	ds_write2_b32 v254, v139, v136 offset0:136 offset1:204
	v_mfma_f32_4x4x4_16b_bf16 v[188:191], v[116:117], v[62:63], v[188:191] cbsz:4 abid:4
	v_mfma_f32_4x4x4_16b_bf16 v[194:197], v[116:117], v[70:71], v[194:197] cbsz:4 abid:4
	v_fma_f32 v200, v150, v199, v200
	v_fma_f32 v204, v150, v203, v204
	v_mfma_f32_4x4x4_16b_bf16 v[246:249], v[172:173], v[78:79], v[246:249] cbsz:4 abid:7
	v_fma_f32 v200, v16, v203, v200
	v_fma_f32 v204, v17, v199, v204
	v_mfma_f32_4x4x4_16b_bf16 v[250:253], v[172:173], v[86:87], v[250:253] cbsz:4 abid:7
	v_fma_f32 v239, v152, v240, v239
	v_fma_f32 v243, v152, v244, v243
	v_mfma_f32_4x4x4_16b_bf16 v[188:191], v[116:117], v[64:65], v[188:191] cbsz:4 abid:8
	v_fma_f32 v239, v36, v244, v239
	v_fma_f32 v243, v37, v240, v243
	v_mfma_f32_4x4x4_16b_bf16 v[194:197], v[116:117], v[72:73], v[194:197] cbsz:4 abid:8
	v_cvt_pk_bf16_f32 v132, v200, v204
	v_cvt_pk_bf16_f32 v143, v239, v243
	v_mfma_f32_4x4x4_16b_bf16 v[246:249], v[172:173], v[80:81], v[246:249] cbsz:4 abid:11
	v_mfma_f32_4x4x4_16b_bf16 v[250:253], v[172:173], v[88:89], v[250:253] cbsz:4 abid:11
	v_fma_f32 v201, v150, v200, v201
	v_fma_f32 v205, v150, v204, v205
	v_mfma_f32_4x4x4_16b_bf16 v[188:191], v[116:117], v[66:67], v[188:191] cbsz:4 abid:12
	v_fma_f32 v201, v16, v204, v201
	v_fma_f32 v205, v17, v200, v205
	v_mfma_f32_4x4x4_16b_bf16 v[194:197], v[116:117], v[74:75], v[194:197] cbsz:4 abid:12
	v_fma_f32 v238, v152, v239, v238
	v_fma_f32 v242, v152, v243, v242
	v_mfma_f32_4x4x4_16b_bf16 v[246:249], v[172:173], v[82:83], v[246:249] cbsz:4 abid:15
	v_fma_f32 v238, v36, v243, v238
	v_fma_f32 v242, v37, v239, v242
	v_mfma_f32_4x4x4_16b_bf16 v[250:253], v[172:173], v[90:91], v[250:253] cbsz:4 abid:15
	v_cvt_pk_bf16_f32 v135, v201, v205
	v_cvt_pk_bf16_f32 v187, v238, v242
	ds_write2_b32 v193, v132, v135 offset0:136 offset1:204
	ds_write2_b32 v254, v187, v143 offset0:0 offset1:68
	v_fma_f32 v206, v150, v201, v206
	v_fma_f32 v210, v150, v205, v210
	v_fma_f32 v206, v16, v205, v206
	v_fma_f32 v210, v17, v201, v210
	v_fma_f32 v233, v152, v238, v233
	v_fma_f32 v237, v152, v242, v237
	v_fma_f32 v233, v36, v242, v233
	v_fma_f32 v237, v37, v238, v237
	v_cvt_pk_bf16_f32 v128, v206, v210
	v_cvt_pk_bf16_f32 v136, v233, v237
	v_add_u32_e32 v193, 0x3080, v103
	v_add_u32_e32 v254, 0x3d40, v103
	v_fma_f32 v207, v150, v206, v207
	v_fma_f32 v211, v150, v210, v211
	v_mfma_f32_4x4x4_16b_bf16 v[198:201], v[116:117], v[60:61], 0 cbsz:4 abid:1
	v_fma_f32 v207, v16, v210, v207
	v_fma_f32 v211, v17, v206, v211
	v_mfma_f32_4x4x4_16b_bf16 v[202:205], v[116:117], v[68:69], 0 cbsz:4 abid:1
	v_fma_f32 v232, v152, v233, v232
	v_fma_f32 v236, v152, v237, v236
	v_mfma_f32_4x4x4_16b_bf16 v[238:241], v[172:173], v[76:77], 0 cbsz:4 abid:2
	v_fma_f32 v232, v36, v237, v232
	v_fma_f32 v236, v37, v233, v236
	v_mfma_f32_4x4x4_16b_bf16 v[242:245], v[172:173], v[84:85], 0 cbsz:4 abid:2
	v_cvt_pk_bf16_f32 v131, v207, v211
	v_cvt_pk_bf16_f32 v139, v232, v236
	ds_write2_b32 v193, v128, v131 offset0:0 offset1:68
	ds_write2_b32 v254, v139, v136 offset0:136 offset1:204
	v_mfma_f32_4x4x4_16b_bf16 v[198:201], v[116:117], v[62:63], v[198:201] cbsz:4 abid:5
	v_mfma_f32_4x4x4_16b_bf16 v[202:205], v[116:117], v[70:71], v[202:205] cbsz:4 abid:5
	v_fma_f32 v208, v150, v207, v208
	v_fma_f32 v212, v150, v211, v212
	v_mfma_f32_4x4x4_16b_bf16 v[238:241], v[172:173], v[78:79], v[238:241] cbsz:4 abid:6
	v_fma_f32 v208, v16, v211, v208
	v_fma_f32 v212, v17, v207, v212
	v_mfma_f32_4x4x4_16b_bf16 v[242:245], v[172:173], v[86:87], v[242:245] cbsz:4 abid:6
	v_fma_f32 v231, v152, v232, v231
	v_fma_f32 v235, v152, v236, v235
	v_mfma_f32_4x4x4_16b_bf16 v[198:201], v[116:117], v[64:65], v[198:201] cbsz:4 abid:9
	v_fma_f32 v231, v36, v236, v231
	v_fma_f32 v235, v37, v232, v235
	v_mfma_f32_4x4x4_16b_bf16 v[202:205], v[116:117], v[72:73], v[202:205] cbsz:4 abid:9
	v_cvt_pk_bf16_f32 v132, v208, v212
	v_cvt_pk_bf16_f32 v143, v231, v235
	v_mfma_f32_4x4x4_16b_bf16 v[238:241], v[172:173], v[80:81], v[238:241] cbsz:4 abid:10
	v_mfma_f32_4x4x4_16b_bf16 v[242:245], v[172:173], v[88:89], v[242:245] cbsz:4 abid:10
	v_fma_f32 v209, v150, v208, v209
	v_fma_f32 v213, v150, v212, v213
	v_mfma_f32_4x4x4_16b_bf16 v[198:201], v[116:117], v[66:67], v[198:201] cbsz:4 abid:13
	v_fma_f32 v209, v16, v212, v209
	v_fma_f32 v213, v17, v208, v213
	v_mfma_f32_4x4x4_16b_bf16 v[202:205], v[116:117], v[74:75], v[202:205] cbsz:4 abid:13
	v_fma_f32 v230, v152, v231, v230
	v_fma_f32 v234, v152, v235, v234
	v_mfma_f32_4x4x4_16b_bf16 v[238:241], v[172:173], v[82:83], v[238:241] cbsz:4 abid:14
	v_fma_f32 v230, v36, v235, v230
	v_fma_f32 v234, v37, v231, v234
	v_mfma_f32_4x4x4_16b_bf16 v[242:245], v[172:173], v[90:91], v[242:245] cbsz:4 abid:14
	v_cvt_pk_bf16_f32 v135, v209, v213
	v_cvt_pk_bf16_f32 v187, v230, v234
	ds_write2_b32 v193, v132, v135 offset0:136 offset1:204
	ds_write2_b32 v254, v187, v143 offset0:0 offset1:68
	v_fma_f32 v214, v150, v209, v214
	v_fma_f32 v218, v150, v213, v218
	v_fma_f32 v214, v16, v213, v214
	v_fma_f32 v218, v17, v209, v218
	v_fma_f32 v225, v152, v230, v225
	v_fma_f32 v229, v152, v234, v229
	v_fma_f32 v225, v36, v234, v225
	v_fma_f32 v229, v37, v230, v229
	v_cvt_pk_bf16_f32 v128, v214, v218
	v_cvt_pk_bf16_f32 v136, v225, v229
; #define LAS __attribute__((address_space(3)))
; __device__ __forceinline__ void s5_out_phase(LAS unsigned char* lds, const bf16_t* UZ, const unsigned char* ws, const float* dskip, bf16_t* YG) {
;     ...
; #pragma unroll
;             for (int nt = 0; nt < 8; ++nt) {
;                 const f32x4 z = {0.f, 0.f, 0.f, 0.f};
;                 const f32x4 cf = __builtin_amdgcn_mfma_f32_16x16x16bf16_1k(Uf[mf], Bf[0][nt], z, 0, 0, 0);
;                 const f32x4 cb = __builtin_amdgcn_mfma_f32_16x16x16bf16_1k(Uf[mb], Bf[1][nt], z, 0, 0, 0);
;                 u32x2 wf, wb; wf.x = pk2(cf[0], cf[1]); wf.y = pk2(cf[2], cf[3]); wb.x = pk2(cb[0], cb[1]); wb.y = pk2(cb[2], cb[3]);
;                 *(LAS u32x2*)(wl + nt * 640 + wofs) = wf;
;                 *(LAS u32x2*)(wl + BUT_BYTES + nt * 640 + wofs) = wb;
;             }
;             WAVE_LDS_FENCE();
;             const LAS unsigned char* rp = wl + lane * 80;
;             const u32x4 fre0 = *(const LAS u32x4*)(rp), fre1 = *(const LAS u32x4*)(rp + 16), fim0 = *(const LAS u32x4*)(rp + 32), fim1 = *(const LAS u32x4*)(rp + 48);
;             const u32x4 bre0 = *(const LAS u32x4*)(rp + BUT_BYTES), bre1 = *(const LAS u32x4*)(rp + BUT_BYTES + 16), bim0 = *(const LAS u32x4*)(rp + BUT_BYTES + 32), bim1 = *(const LAS u32x4*)(rp + BUT_BYTES + 48);
;             LAS unsigned char* xf = wl + 2 * BUT_BYTES; LAS unsigned char* xbk = xf + XB_BYTES;
; #pragma unroll
;             for (int rr = 0; rr < 16; ++rr) {
;                 const int r = rr, rb = 15 - rr;
;                 { const f32x2 bb = {bf_at(fre0, fre1, r), bf_at(fim0, fim1, r)};
;                   const f32x2 n2 = cmac((f32x2){xfr, xfi}, (f32x2){ap[0].x, ap[0].x}, (f32x2){-ap[0].y, ap[0].y}, bb); xfr = n2.x; xfi = n2.y;
;                   *(LAS unsigned*)(xf + r * XB_PITCH + lane * 4) = pk2(n2.x, n2.y); }
;                 { const f32x2 bb = {bf_at(bre0, bre1, rb), bf_at(bim0, bim1, rb)};
;                   const f32x2 n2 = cmac((f32x2){xbr, xbi}, (f32x2){ap[1].x, ap[1].x}, (f32x2){-ap[1].y, ap[1].y}, bb); xbr = n2.x; xbi = n2.y;
;                   *(LAS unsigned*)(xbk + rb * XB_PITCH + lane * 4) = pk2(n2.x, n2.y); }
;             }
;             WAVE_LDS_FENCE();
; #pragma unroll
;             for (int ks = 0; ks < 4; ++ks) {
;                 const bf16x8 Xf = *(const LAS bf16x8*)(xf + fr * XB_PITCH + (8 * fq + 32 * ks) * 2);
	v_add_u32_e32 v193, 0x34c0, v103
	v_add_u32_e32 v254, 0x3900, v103
	v_fma_f32 v215, v150, v214, v215
	v_fma_f32 v219, v150, v218, v219
	v_fma_f32 v215, v16, v218, v215
	v_fma_f32 v219, v17, v214, v219
	v_fma_f32 v224, v152, v225, v224
	v_fma_f32 v228, v152, v229, v228
	v_fma_f32 v224, v36, v229, v224
	v_fma_f32 v228, v37, v225, v228
	v_cvt_pk_bf16_f32 v131, v215, v219
	v_cvt_pk_bf16_f32 v139, v224, v228
	ds_write2_b32 v193, v128, v131 offset0:0 offset1:68
	ds_write2_b32 v254, v139, v136 offset0:136 offset1:204
	v_fma_f32 v216, v150, v215, v216
	v_fma_f32 v220, v150, v219, v220
	v_fma_f32 v216, v16, v219, v216
	v_fma_f32 v220, v17, v215, v220
	v_fma_f32 v223, v152, v224, v223
	v_fma_f32 v227, v152, v228, v227
	v_fma_f32 v223, v36, v228, v223
	v_fma_f32 v227, v37, v224, v227
	v_cvt_pk_bf16_f32 v132, v216, v220
	v_cvt_pk_bf16_f32 v143, v223, v227
	v_fma_f32 v217, v150, v216, v217
	v_fma_f32 v221, v150, v220, v221
	v_fma_f32 v217, v16, v220, v217
	v_fma_f32 v221, v17, v216, v221
	v_fma_f32 v222, v152, v223, v222
	v_fma_f32 v226, v152, v227, v226
	v_fma_f32 v222, v36, v227, v222
	v_fma_f32 v226, v37, v223, v226
	v_cvt_pk_bf16_f32 v135, v217, v221
	v_cvt_pk_bf16_f32 v187, v222, v226
	ds_write2_b32 v193, v132, v135 offset0:136 offset1:204
	ds_write2_b32 v254, v187, v143 offset0:0 offset1:68
	v_mov_b32_e32 v114, v217
	v_mov_b32_e32 v119, v221
	v_mov_b32_e32 v121, v222
	v_mov_b32_e32 v127, v226
	ds_read_b128 v[206:209], v110 offset:10240
	ds_read_b128 v[210:213], v110 offset:10304
	ds_read_b128 v[214:217], v110 offset:10368
	ds_read_b128 v[218:221], v110 offset:10432
	ds_read_b128 v[222:225], v110 offset:14592
	ds_read_b128 v[226:229], v110 offset:14656
	ds_read_b128 v[230:233], v110 offset:14720
	ds_read_b128 v[234:237], v110 offset:14784
	s_waitcnt lgkmcnt(7)
	v_mfma_f32_16x16x32_bf16 v[52:55], v[0:3], v[206:209], v[52:55]
	s_waitcnt lgkmcnt(3)
	v_mfma_f32_16x16x32_bf16 v[56:59], v[20:23], v[222:225], v[56:59]
	v_mfma_f32_16x16x32_bf16 v[52:55], v[4:7], v[210:213], v[52:55]
	s_waitcnt lgkmcnt(2)
	v_mfma_f32_16x16x32_bf16 v[56:59], v[24:27], v[226:229], v[56:59]
	v_mfma_f32_16x16x32_bf16 v[52:55], v[8:11], v[214:217], v[52:55]
	s_waitcnt lgkmcnt(1)
	v_mfma_f32_16x16x32_bf16 v[56:59], v[28:31], v[230:233], v[56:59]
	v_mfma_f32_16x16x32_bf16 v[52:55], v[12:15], v[218:221], v[52:55]
	s_waitcnt lgkmcnt(0)
	v_mfma_f32_16x16x32_bf16 v[56:59], v[32:35], v[234:237], v[56:59]
	v_mfma_f32_4x4x4_16b_bf16 v[206:209], v[116:117], v[60:61], 0 cbsz:4 abid:2
	v_mfma_f32_4x4x4_16b_bf16 v[210:213], v[116:117], v[68:69], 0 cbsz:4 abid:2
	v_mfma_f32_4x4x4_16b_bf16 v[214:217], v[116:117], v[60:61], 0 cbsz:4 abid:3
	v_mfma_f32_4x4x4_16b_bf16 v[218:221], v[116:117], v[68:69], 0 cbsz:4 abid:3
	v_mfma_f32_4x4x4_16b_bf16 v[222:225], v[172:173], v[76:77], 0 cbsz:4 abid:0
	v_mfma_f32_4x4x4_16b_bf16 v[226:229], v[172:173], v[84:85], 0 cbsz:4 abid:0
	v_mfma_f32_4x4x4_16b_bf16 v[230:233], v[172:173], v[76:77], 0 cbsz:4 abid:1
	v_mfma_f32_4x4x4_16b_bf16 v[234:237], v[172:173], v[84:85], 0 cbsz:4 abid:1
	v_mfma_f32_4x4x4_16b_bf16 v[206:209], v[116:117], v[62:63], v[206:209] cbsz:4 abid:6
	v_mfma_f32_4x4x4_16b_bf16 v[210:213], v[116:117], v[70:71], v[210:213] cbsz:4 abid:6
	v_mfma_f32_4x4x4_16b_bf16 v[214:217], v[116:117], v[62:63], v[214:217] cbsz:4 abid:7
	v_mfma_f32_4x4x4_16b_bf16 v[218:221], v[116:117], v[70:71], v[218:221] cbsz:4 abid:7
	v_mfma_f32_4x4x4_16b_bf16 v[222:225], v[172:173], v[78:79], v[222:225] cbsz:4 abid:4
	v_mfma_f32_4x4x4_16b_bf16 v[226:229], v[172:173], v[86:87], v[226:229] cbsz:4 abid:4
	v_mfma_f32_4x4x4_16b_bf16 v[230:233], v[172:173], v[78:79], v[230:233] cbsz:4 abid:5
	v_mfma_f32_4x4x4_16b_bf16 v[234:237], v[172:173], v[86:87], v[234:237] cbsz:4 abid:5
	v_mfma_f32_4x4x4_16b_bf16 v[206:209], v[116:117], v[64:65], v[206:209] cbsz:4 abid:10
	v_mfma_f32_4x4x4_16b_bf16 v[210:213], v[116:117], v[72:73], v[210:213] cbsz:4 abid:10
	v_mfma_f32_4x4x4_16b_bf16 v[214:217], v[116:117], v[64:65], v[214:217] cbsz:4 abid:11
	v_mfma_f32_4x4x4_16b_bf16 v[218:221], v[116:117], v[72:73], v[218:221] cbsz:4 abid:11
	v_mfma_f32_4x4x4_16b_bf16 v[222:225], v[172:173], v[80:81], v[222:225] cbsz:4 abid:8
	v_mfma_f32_4x4x4_16b_bf16 v[226:229], v[172:173], v[88:89], v[226:229] cbsz:4 abid:8
	v_mfma_f32_4x4x4_16b_bf16 v[230:233], v[172:173], v[80:81], v[230:233] cbsz:4 abid:9
	v_mfma_f32_4x4x4_16b_bf16 v[234:237], v[172:173], v[88:89], v[234:237] cbsz:4 abid:9
	v_mfma_f32_4x4x4_16b_bf16 v[206:209], v[116:117], v[66:67], v[206:209] cbsz:4 abid:14
	v_mfma_f32_4x4x4_16b_bf16 v[210:213], v[116:117], v[74:75], v[210:213] cbsz:4 abid:14
	v_mfma_f32_4x4x4_16b_bf16 v[214:217], v[116:117], v[66:67], v[214:217] cbsz:4 abid:15
	v_mfma_f32_4x4x4_16b_bf16 v[218:221], v[116:117], v[74:75], v[218:221] cbsz:4 abid:15
	v_mfma_f32_4x4x4_16b_bf16 v[222:225], v[172:173], v[82:83], v[222:225] cbsz:4 abid:12
	v_mfma_f32_4x4x4_16b_bf16 v[226:229], v[172:173], v[90:91], v[226:229] cbsz:4 abid:12
	v_mfma_f32_4x4x4_16b_bf16 v[230:233], v[172:173], v[82:83], v[230:233] cbsz:4 abid:13
	v_mfma_f32_4x4x4_16b_bf16 v[234:237], v[172:173], v[90:91], v[234:237] cbsz:4 abid:13
	v_fma_f32 v188, v150, v114, v188
	v_fma_f32 v194, v150, v119, v194
	v_fma_f32 v188, v16, v119, v188
	v_fma_f32 v194, v17, v114, v194
	v_fma_f32 v249, v152, v121, v249
	v_fma_f32 v253, v152, v127, v253
	v_fma_f32 v249, v36, v127, v249
	v_fma_f32 v253, v37, v121, v253
	v_cvt_pk_bf16_f32 v128, v188, v194
	v_cvt_pk_bf16_f32 v136, v249, v253
	v_add_u32_e32 v193, 0x2800, v103
	v_add_u32_e32 v254, 0x45c0, v103
	v_fma_f32 v189, v150, v188, v189
	v_fma_f32 v195, v150, v194, v195
	v_fma_f32 v189, v16, v194, v189
	v_fma_f32 v195, v17, v188, v195
; #define LAS __attribute__((address_space(3)))
; __device__ __forceinline__ unsigned pk2(float lo, float hi) { f32x2 v = {lo, hi}; nbf2 r = __builtin_convertvector(v, nbf2); return __builtin_bit_cast(unsigned, r); }
; #define WAVE_LDS_FENCE() asm volatile("s_waitcnt lgkmcnt(0)" ::: "memory")
; __device__ __forceinline__ float bf_at(const u32x4& lo, const u32x4& hi, int r) { const unsigned w = (r < 8 ? lo : hi)[(r & 7) >> 1]; return (r & 1) ? bf_hi(w) : bf_lo(w); }
; __device__ __forceinline__ void s5_out_phase(LAS unsigned char* lds, const bf16_t* UZ, const unsigned char* ws, const float* dskip, bf16_t* YG) {
;     ...
; #pragma unroll
;             for (int rr = 0; rr < 16; ++rr) {
;                 const int r = rr, rb = 15 - rr;
;                 { const f32x2 bb = {bf_at(fre0, fre1, r), bf_at(fim0, fim1, r)};
;                   const f32x2 n2 = cmac((f32x2){xfr, xfi}, (f32x2){ap[0].x, ap[0].x}, (f32x2){-ap[0].y, ap[0].y}, bb); xfr = n2.x; xfi = n2.y;
;                   *(LAS unsigned*)(xf + r * XB_PITCH + lane * 4) = pk2(n2.x, n2.y); }
;                 { const f32x2 bb = {bf_at(bre0, bre1, rb), bf_at(bim0, bim1, rb)};
;                   const f32x2 n2 = cmac((f32x2){xbr, xbi}, (f32x2){ap[1].x, ap[1].x}, (f32x2){-ap[1].y, ap[1].y}, bb); xbr = n2.x; xbi = n2.y;
;                   *(LAS unsigned*)(xbk + rb * XB_PITCH + lane * 4) = pk2(n2.x, n2.y); }
;             }
;             WAVE_LDS_FENCE();
	v_fma_f32 v248, v152, v249, v248
	v_fma_f32 v252, v152, v253, v252
	v_fma_f32 v248, v36, v253, v248
	v_fma_f32 v252, v37, v249, v252
	v_cvt_pk_bf16_f32 v131, v189, v195
	v_cvt_pk_bf16_f32 v139, v248, v252
	ds_write2_b32 v193, v128, v131 offset0:0 offset1:68
	ds_write2_b32 v254, v139, v136 offset0:136 offset1:204
	v_fma_f32 v190, v150, v189, v190
	v_fma_f32 v196, v150, v195, v196
	v_fma_f32 v190, v16, v195, v190
	v_fma_f32 v196, v17, v189, v196
	v_fma_f32 v247, v152, v248, v247
	v_fma_f32 v251, v152, v252, v251
	v_fma_f32 v247, v36, v252, v247
	v_fma_f32 v251, v37, v248, v251
	v_cvt_pk_bf16_f32 v132, v190, v196
	v_cvt_pk_bf16_f32 v143, v247, v251
	v_fma_f32 v191, v150, v190, v191
	v_fma_f32 v197, v150, v196, v197
	v_fma_f32 v191, v16, v196, v191
	v_fma_f32 v197, v17, v190, v197
	v_fma_f32 v246, v152, v247, v246
	v_fma_f32 v250, v152, v251, v250
	v_fma_f32 v246, v36, v251, v246
	v_fma_f32 v250, v37, v247, v250
	v_cvt_pk_bf16_f32 v135, v191, v197
	v_cvt_pk_bf16_f32 v187, v246, v250
	ds_write2_b32 v193, v132, v135 offset0:136 offset1:204
	ds_write2_b32 v254, v187, v143 offset0:0 offset1:68
	v_fma_f32 v198, v150, v191, v198
	v_fma_f32 v202, v150, v197, v202
	v_fma_f32 v198, v16, v197, v198
	v_fma_f32 v202, v17, v191, v202
	v_fma_f32 v241, v152, v246, v241
	v_fma_f32 v245, v152, v250, v245
	v_fma_f32 v241, v36, v250, v241
	v_fma_f32 v245, v37, v246, v245
	v_cvt_pk_bf16_f32 v128, v198, v202
	v_cvt_pk_bf16_f32 v136, v241, v245
	v_add_u32_e32 v193, 0x2c40, v103
	v_add_u32_e32 v254, 0x4180, v103
	v_fma_f32 v199, v150, v198, v199
	v_fma_f32 v203, v150, v202, v203
	v_fma_f32 v199, v16, v202, v199
	v_fma_f32 v203, v17, v198, v203
	v_fma_f32 v240, v152, v241, v240
	v_fma_f32 v244, v152, v245, v244
	v_fma_f32 v240, v36, v245, v240
	v_fma_f32 v244, v37, v241, v244
	v_cvt_pk_bf16_f32 v131, v199, v203
	v_cvt_pk_bf16_f32 v139, v240, v244
	ds_write2_b32 v193, v128, v131 offset0:0 offset1:68
	ds_write2_b32 v254, v139, v136 offset0:136 offset1:204
	v_fma_f32 v200, v150, v199, v200
	v_fma_f32 v204, v150, v203, v204
	v_fma_f32 v200, v16, v203, v200
	v_fma_f32 v204, v17, v199, v204
	v_fma_f32 v239, v152, v240, v239
	v_fma_f32 v243, v152, v244, v243
	v_fma_f32 v239, v36, v244, v239
	v_fma_f32 v243, v37, v240, v243
	v_cvt_pk_bf16_f32 v132, v200, v204
	v_cvt_pk_bf16_f32 v143, v239, v243
	v_fma_f32 v201, v150, v200, v201
	v_fma_f32 v205, v150, v204, v205
	v_fma_f32 v201, v16, v204, v201
	v_fma_f32 v205, v17, v200, v205
	v_fma_f32 v238, v152, v239, v238
	v_fma_f32 v242, v152, v243, v242
	v_fma_f32 v238, v36, v243, v238
	v_fma_f32 v242, v37, v239, v242
	v_cvt_pk_bf16_f32 v135, v201, v205
	v_cvt_pk_bf16_f32 v187, v238, v242
	ds_write2_b32 v193, v132, v135 offset0:136 offset1:204
	ds_write2_b32 v254, v187, v143 offset0:0 offset1:68
	v_fma_f32 v206, v150, v201, v206
	v_fma_f32 v210, v150, v205, v210
	v_fma_f32 v206, v16, v205, v206
	v_fma_f32 v210, v17, v201, v210
	v_fma_f32 v233, v152, v238, v233
	v_fma_f32 v237, v152, v242, v237
	v_fma_f32 v233, v36, v242, v233
	v_fma_f32 v237, v37, v238, v237
	v_cvt_pk_bf16_f32 v128, v206, v210
	v_cvt_pk_bf16_f32 v136, v233, v237
	v_add_u32_e32 v193, 0x3080, v103
	v_add_u32_e32 v254, 0x3d40, v103
	v_fma_f32 v207, v150, v206, v207
	v_fma_f32 v211, v150, v210, v211
	v_fma_f32 v207, v16, v210, v207
	v_fma_f32 v211, v17, v206, v211
	v_fma_f32 v232, v152, v233, v232
	v_fma_f32 v236, v152, v237, v236
	v_fma_f32 v232, v36, v237, v232
	v_fma_f32 v236, v37, v233, v236
	v_cvt_pk_bf16_f32 v131, v207, v211
	v_cvt_pk_bf16_f32 v139, v232, v236
	ds_write2_b32 v193, v128, v131 offset0:0 offset1:68
	ds_write2_b32 v254, v139, v136 offset0:136 offset1:204
	v_fma_f32 v208, v150, v207, v208
	v_fma_f32 v212, v150, v211, v212
	v_fma_f32 v208, v16, v211, v208
	v_fma_f32 v212, v17, v207, v212
	v_fma_f32 v231, v152, v232, v231
	v_fma_f32 v235, v152, v236, v235
	v_fma_f32 v231, v36, v236, v231
	v_fma_f32 v235, v37, v232, v235
	v_cvt_pk_bf16_f32 v132, v208, v212
	v_cvt_pk_bf16_f32 v143, v231, v235
	v_fma_f32 v209, v150, v208, v209
	v_fma_f32 v213, v150, v212, v213
	v_fma_f32 v209, v16, v212, v209
	v_fma_f32 v213, v17, v208, v213
	v_fma_f32 v230, v152, v231, v230
	v_fma_f32 v234, v152, v235, v234
	v_fma_f32 v230, v36, v235, v230
	v_fma_f32 v234, v37, v231, v234
	v_cvt_pk_bf16_f32 v135, v209, v213
	v_cvt_pk_bf16_f32 v187, v230, v234
	ds_write2_b32 v193, v132, v135 offset0:136 offset1:204
	ds_write2_b32 v254, v187, v143 offset0:0 offset1:68
	v_fma_f32 v214, v150, v209, v214
	v_fma_f32 v218, v150, v213, v218
	v_fma_f32 v214, v16, v213, v214
	v_fma_f32 v218, v17, v209, v218
	v_fma_f32 v225, v152, v230, v225
	v_fma_f32 v229, v152, v234, v229
	v_fma_f32 v225, v36, v234, v225
	v_fma_f32 v229, v37, v230, v229
	v_cvt_pk_bf16_f32 v128, v214, v218
	v_cvt_pk_bf16_f32 v136, v225, v229
	v_add_u32_e32 v193, 0x34c0, v103
	v_add_u32_e32 v254, 0x3900, v103
	v_fma_f32 v215, v150, v214, v215
	v_fma_f32 v219, v150, v218, v219
	v_fma_f32 v215, v16, v218, v215
	v_fma_f32 v219, v17, v214, v219
	v_fma_f32 v224, v152, v225, v224
	v_fma_f32 v228, v152, v229, v228
	v_fma_f32 v224, v36, v229, v224
	v_fma_f32 v228, v37, v225, v228
	v_cvt_pk_bf16_f32 v131, v215, v219
	v_cvt_pk_bf16_f32 v139, v224, v228
	ds_write2_b32 v193, v128, v131 offset0:0 offset1:68
	ds_write2_b32 v254, v139, v136 offset0:136 offset1:204
	v_fma_f32 v216, v150, v215, v216
	v_fma_f32 v220, v150, v219, v220
	v_fma_f32 v216, v16, v219, v216
	v_fma_f32 v220, v17, v215, v220
	v_fma_f32 v223, v152, v224, v223
	v_fma_f32 v227, v152, v228, v227
	v_fma_f32 v223, v36, v228, v223
	v_fma_f32 v227, v37, v224, v227
	v_cvt_pk_bf16_f32 v132, v216, v220
	v_cvt_pk_bf16_f32 v143, v223, v227
	v_fma_f32 v217, v150, v216, v217
	v_fma_f32 v221, v150, v220, v221
	v_fma_f32 v217, v16, v220, v217
	v_fma_f32 v221, v17, v216, v221
	v_fma_f32 v222, v152, v223, v222
	v_fma_f32 v226, v152, v227, v226
	v_fma_f32 v222, v36, v227, v222
	v_fma_f32 v226, v37, v223, v226
	v_cvt_pk_bf16_f32 v135, v217, v221
	v_cvt_pk_bf16_f32 v187, v222, v226
	ds_write2_b32 v193, v132, v135 offset0:136 offset1:204
	ds_write2_b32 v254, v187, v143 offset0:0 offset1:68
	v_mov_b32_e32 v114, v217
	v_mov_b32_e32 v119, v221
	v_mov_b32_e32 v121, v222
	v_mov_b32_e32 v127, v226
	ds_read_b128 v[206:209], v110 offset:10240
	ds_read_b128 v[210:213], v110 offset:10304
	ds_read_b128 v[214:217], v110 offset:10368
	ds_read_b128 v[218:221], v110 offset:10432
	ds_read_b128 v[222:225], v110 offset:14592
	ds_read_b128 v[226:229], v110 offset:14656
	ds_read_b128 v[230:233], v110 offset:14720
	ds_read_b128 v[234:237], v110 offset:14784
	s_waitcnt lgkmcnt(7)
; #define LAS __attribute__((address_space(3)))
; __device__ __forceinline__ unsigned pk2(float lo, float hi) { f32x2 v = {lo, hi}; nbf2 r = __builtin_convertvector(v, nbf2); return __builtin_bit_cast(unsigned, r); }
; __device__ __forceinline__ float bf_lo(unsigned w) { return __uint_as_float(w << 16); }
; __device__ __forceinline__ float bf_hi(unsigned w) { return __uint_as_float(w & 0xffff0000u); }
; __device__ __forceinline__ void s5_out_phase(LAS unsigned char* lds, const bf16_t* UZ, const unsigned char* ws, const float* dskip, bf16_t* YG) {
;     ...
; #pragma unroll
;             for (int ks = 0; ks < 4; ++ks) {
;                 const bf16x8 Xf = *(const LAS bf16x8*)(xf + fr * XB_PITCH + (8 * fq + 32 * ks) * 2);
;                 const bf16x8 Xb = *(const LAS bf16x8*)(xbk + fr * XB_PITCH + (8 * fq + 32 * ks) * 2);
;                 accY[mf] = __builtin_amdgcn_mfma_f32_16x16x32_bf16(Cf[0][ks], Xf, accY[mf], 0, 0, 0);
;                 accY[mb] = __builtin_amdgcn_mfma_f32_16x16x32_bf16(Cf[1][ks], Xb, accY[mb], 0, 0, 0);
;             }
;         }
; #pragma unroll
;         for (int m = 0; m < 4; ++m) {
;             const unsigned u0 = (unsigned)(unsigned short)Uf[m][0] | ((unsigned)(unsigned short)Uf[m][1] << 16), u1 = (unsigned)(unsigned short)Uf[m][2] | ((unsigned)(unsigned short)Uf[m][3] << 16);
;             const float y0 = gelu_f(accY[m][0] + dsk[0] * bf_lo(u0)), y1 = gelu_f(accY[m][1] + dsk[1] * bf_hi(u0));
;             const float y2 = gelu_f(accY[m][2] + dsk[2] * bf_lo(u1)), y3 = gelu_f(accY[m][3] + dsk[3] * bf_hi(u1));
;             u32x2 w; w.x = pk2(y0, y1); w.y = pk2(y2, y3);
;             *(u32x2*)(YG + (size_t)(rowbase + 16 * m + fr) * D + 16 * g + 4 * fq) = w;
;         }
	v_mfma_f32_16x16x32_bf16 v[44:47], v[0:3], v[206:209], v[44:47]
	s_waitcnt lgkmcnt(3)
	v_mfma_f32_16x16x32_bf16 v[48:51], v[20:23], v[222:225], v[48:51]
	v_mfma_f32_16x16x32_bf16 v[44:47], v[4:7], v[210:213], v[44:47]
	s_waitcnt lgkmcnt(2)
	v_mfma_f32_16x16x32_bf16 v[48:51], v[24:27], v[226:229], v[48:51]
	v_mfma_f32_16x16x32_bf16 v[44:47], v[8:11], v[214:217], v[44:47]
	s_waitcnt lgkmcnt(1)
	v_mfma_f32_16x16x32_bf16 v[48:51], v[28:31], v[230:233], v[48:51]
	v_mfma_f32_16x16x32_bf16 v[44:47], v[12:15], v[218:221], v[44:47]
	s_waitcnt lgkmcnt(0)
	v_mfma_f32_16x16x32_bf16 v[48:51], v[32:35], v[234:237], v[48:51]
	v_ashrrev_i32_e32 v167, 31, v166
	s_nop 7
	s_nop 4
	v_lshlrev_b32_e32 v188, 16, v172
	v_and_b32_e32 v189, 0xffff0000, v172
	s_waitcnt vmcnt(0)
	v_pk_fma_f32 v[188:189], v[40:41], v[188:189], v[48:49]
	v_lshlrev_b32_e32 v172, 16, v173
	v_fma_f32 v48, |v188|, s21, 1.0
	v_rcp_f32_e32 v190, v48
	v_fma_f32 v48, |v189|, s21, 1.0
	v_rcp_f32_e32 v191, v48
	v_pk_mul_f32 v[194:195], v[188:189], v[188:189]
	v_and_b32_e32 v173, 0xffff0000, v173
	v_mul_f32_e32 v48, 0xbf38aa3b, v194
	v_exp_f32_e32 v194, v48
	v_mov_b64_e32 v[48:49], s[4:5]
	v_pk_fma_f32 v[196:197], v[190:191], s[2:3], v[48:49] op_sel_hi:[1,0,0]
	v_mul_f32_e32 v114, 0xbf38aa3b, v195
	v_pk_fma_f32 v[196:197], v[190:191], v[196:197], s[8:9] op_sel_hi:[1,1,0]
	v_exp_f32_e32 v195, v114
	v_pk_fma_f32 v[196:197], v[190:191], v[196:197], s[20:21] op_sel_hi:[1,1,0]
	v_pk_fma_f32 v[50:51], v[42:43], v[172:173], v[50:51]
	v_pk_fma_f32 v[196:197], v[190:191], v[196:197], s[22:23] op_sel_hi:[1,1,0]
	v_fma_f32 v121, |v50|, s21, 1.0
	v_pk_mul_f32 v[190:191], v[190:191], v[196:197]
	v_rcp_f32_e32 v172, v121
	v_fma_f32 v121, |v51|, s21, 1.0
	v_pk_mul_f32 v[190:191], v[194:195], v[190:191]
	v_rcp_f32_e32 v173, v121
	v_pk_mul_f32 v[194:195], v[188:189], v[190:191]
	v_pk_fma_f32 v[190:191], v[188:189], v[190:191], v[188:189] neg_lo:[1,0,0] neg_hi:[1,0,0]
	v_cmp_gt_f32_e32 vcc, 0, v189
	s_nop 1
	v_cndmask_b32_e32 v114, v191, v195, vcc
	v_cmp_gt_f32_e32 vcc, 0, v188
	v_pk_mul_f32 v[188:189], v[50:51], v[50:51]
	s_nop 0
	v_mul_f32_e32 v121, 0xbf38aa3b, v188
	v_cndmask_b32_e32 v119, v190, v194, vcc
	v_exp_f32_e32 v188, v121
	v_pk_fma_f32 v[190:191], v[172:173], s[2:3], v[48:49] op_sel_hi:[1,0,0]
	v_mul_f32_e32 v121, 0xbf38aa3b, v189
	v_pk_fma_f32 v[190:191], v[172:173], v[190:191], s[8:9] op_sel_hi:[1,1,0]
	v_exp_f32_e32 v189, v121
	v_pk_fma_f32 v[190:191], v[172:173], v[190:191], s[20:21] op_sel_hi:[1,1,0]
	v_cmp_gt_f32_e32 vcc, 0, v51
	v_pk_fma_f32 v[190:191], v[172:173], v[190:191], s[22:23] op_sel_hi:[1,1,0]
	s_nop 0
	v_pk_mul_f32 v[172:173], v[172:173], v[190:191]
	s_nop 0
	v_pk_mul_f32 v[172:173], v[188:189], v[172:173]
	s_nop 0
	v_pk_mul_f32 v[188:189], v[50:51], v[172:173]
	v_pk_fma_f32 v[172:173], v[50:51], v[172:173], v[50:51] neg_lo:[1,0,0] neg_hi:[1,0,0]
	s_nop 0
	v_cndmask_b32_e32 v51, v173, v189, vcc
	v_cmp_gt_f32_e32 vcc, 0, v50
	v_cvt_pk_bf16_f32 v50, v119, v114
	s_nop 0
	v_cndmask_b32_e32 v121, v172, v188, vcc
	v_lshlrev_b64 v[172:173], 11, v[166:167]
	v_cvt_pk_bf16_f32 v51, v121, v51
	v_lshl_add_u64 v[172:173], v[154:155], 0, v[172:173]
	global_store_dwordx2 v[172:173], v[50:51], off
	v_lshlrev_b32_e32 v50, 16, v170
	v_and_b32_e32 v51, 0xffff0000, v170
	v_pk_fma_f32 v[50:51], v[40:41], v[50:51], v[56:57]
	s_nop 0
	v_fma_f32 v56, |v50|, s21, 1.0
	v_fma_f32 v57, |v51|, s21, 1.0
	v_rcp_f32_e32 v56, v56
	v_rcp_f32_e32 v57, v57
	v_pk_mul_f32 v[172:173], v[50:51], v[50:51]
	v_cmp_gt_f32_e32 vcc, 0, v51
	v_mul_f32_e32 v114, 0xbf38aa3b, v172
	v_exp_f32_e32 v172, v114
	v_pk_fma_f32 v[188:189], v[56:57], s[2:3], v[48:49] op_sel_hi:[1,0,0]
	v_mul_f32_e32 v114, 0xbf38aa3b, v173
	v_pk_fma_f32 v[188:189], v[56:57], v[188:189], s[8:9] op_sel_hi:[1,1,0]
	v_exp_f32_e32 v173, v114
	v_pk_fma_f32 v[188:189], v[56:57], v[188:189], s[20:21] op_sel_hi:[1,1,0]
	s_nop 0
	v_pk_fma_f32 v[188:189], v[56:57], v[188:189], s[22:23] op_sel_hi:[1,1,0]
	s_nop 0
	v_pk_mul_f32 v[56:57], v[56:57], v[188:189]
	s_nop 0
	v_pk_mul_f32 v[56:57], v[172:173], v[56:57]
	s_nop 0
	v_pk_mul_f32 v[172:173], v[50:51], v[56:57]
	v_pk_fma_f32 v[56:57], v[50:51], v[56:57], v[50:51] neg_lo:[1,0,0] neg_hi:[1,0,0]
	v_and_b32_e32 v51, 0xffff0000, v171
	v_cndmask_b32_e32 v114, v57, v173, vcc
	v_cmp_gt_f32_e32 vcc, 0, v50
	v_lshlrev_b32_e32 v50, 16, v171
	v_pk_fma_f32 v[50:51], v[42:43], v[50:51], v[58:59]
	v_cndmask_b32_e32 v119, v56, v172, vcc
	v_fma_f32 v56, |v50|, s21, 1.0
	v_fma_f32 v57, |v51|, s21, 1.0
	v_rcp_f32_e32 v56, v56
	v_rcp_f32_e32 v57, v57
	v_pk_mul_f32 v[58:59], v[50:51], v[50:51]
	v_cmp_gt_f32_e32 vcc, 0, v51
	v_mul_f32_e32 v58, 0xbf38aa3b, v58
	v_pk_fma_f32 v[170:171], v[56:57], s[2:3], v[48:49] op_sel_hi:[1,0,0]
	v_mul_f32_e32 v59, 0xbf38aa3b, v59
	v_exp_f32_e32 v58, v58
	v_pk_fma_f32 v[170:171], v[56:57], v[170:171], s[8:9] op_sel_hi:[1,1,0]
	v_exp_f32_e32 v59, v59
	v_pk_fma_f32 v[170:171], v[56:57], v[170:171], s[20:21] op_sel_hi:[1,1,0]
	v_mov_b64_e32 v[172:173], v[174:175]
	v_pk_fma_f32 v[170:171], v[56:57], v[170:171], s[22:23] op_sel_hi:[1,1,0]
	s_nop 0
	v_pk_mul_f32 v[56:57], v[56:57], v[170:171]
	v_mov_b64_e32 v[170:171], v[176:177]
	v_pk_mul_f32 v[56:57], v[58:59], v[56:57]
	s_nop 0
	v_pk_mul_f32 v[58:59], v[50:51], v[56:57]
	v_pk_fma_f32 v[56:57], v[50:51], v[56:57], v[50:51] neg_lo:[1,0,0] neg_hi:[1,0,0]
	s_nop 0
; __device__ __forceinline__ unsigned pk2(float lo, float hi) { f32x2 v = {lo, hi}; nbf2 r = __builtin_convertvector(v, nbf2); return __builtin_bit_cast(unsigned, r); }
; __device__ __forceinline__ float bf_lo(unsigned w) { return __uint_as_float(w << 16); }
; __device__ __forceinline__ float bf_hi(unsigned w) { return __uint_as_float(w & 0xffff0000u); }
; __device__ __forceinline__ void s5_out_phase(LAS unsigned char* lds, const bf16_t* UZ, const unsigned char* ws, const float* dskip, bf16_t* YG) {
;     ...
; #pragma unroll
;         for (int m = 0; m < 4; ++m) {
;             const unsigned u0 = (unsigned)(unsigned short)Uf[m][0] | ((unsigned)(unsigned short)Uf[m][1] << 16), u1 = (unsigned)(unsigned short)Uf[m][2] | ((unsigned)(unsigned short)Uf[m][3] << 16);
;             const float y0 = gelu_f(accY[m][0] + dsk[0] * bf_lo(u0)), y1 = gelu_f(accY[m][1] + dsk[1] * bf_hi(u0));
;             const float y2 = gelu_f(accY[m][2] + dsk[2] * bf_lo(u1)), y3 = gelu_f(accY[m][3] + dsk[3] * bf_hi(u1));
;             u32x2 w; w.x = pk2(y0, y1); w.y = pk2(y2, y3);
;             *(u32x2*)(YG + (size_t)(rowbase + 16 * m + fr) * D + 16 * g + 4 * fq) = w;
;         }
	v_cndmask_b32_e32 v51, v57, v59, vcc
	v_cmp_gt_f32_e32 vcc, 0, v50
	v_cvt_pk_bf16_f32 v50, v119, v114
	s_nop 0
	v_cndmask_b32_e32 v56, v56, v58, vcc
	v_cvt_pk_bf16_f32 v51, v56, v51
	v_add_u32_e32 v56, 16, v166
	v_ashrrev_i32_e32 v57, 31, v56
	v_lshlrev_b64 v[56:57], 11, v[56:57]
	v_lshl_add_u64 v[56:57], v[154:155], 0, v[56:57]
	global_store_dwordx2 v[56:57], v[50:51], off
	v_lshlrev_b32_e32 v50, 16, v168
	v_and_b32_e32 v51, 0xffff0000, v168
	v_pk_fma_f32 v[50:51], v[40:41], v[50:51], v[52:53]
	s_nop 0
	v_fma_f32 v52, |v50|, s21, 1.0
	v_fma_f32 v53, |v51|, s21, 1.0
	v_rcp_f32_e32 v52, v52
	v_rcp_f32_e32 v53, v53
	v_pk_mul_f32 v[56:57], v[50:51], v[50:51]
	v_cmp_gt_f32_e32 vcc, 0, v51
	v_mul_f32_e32 v56, 0xbf38aa3b, v56
	v_pk_fma_f32 v[58:59], v[52:53], s[2:3], v[48:49] op_sel_hi:[1,0,0]
	v_mul_f32_e32 v57, 0xbf38aa3b, v57
	v_exp_f32_e32 v56, v56
	v_pk_fma_f32 v[58:59], v[52:53], v[58:59], s[8:9] op_sel_hi:[1,1,0]
	v_exp_f32_e32 v57, v57
	v_pk_fma_f32 v[58:59], v[52:53], v[58:59], s[20:21] op_sel_hi:[1,1,0]
	s_nop 0
	v_pk_fma_f32 v[58:59], v[52:53], v[58:59], s[22:23] op_sel_hi:[1,1,0]
	s_nop 0
	v_pk_mul_f32 v[52:53], v[52:53], v[58:59]
	s_nop 0
	v_pk_mul_f32 v[52:53], v[56:57], v[52:53]
	s_nop 0
	v_pk_mul_f32 v[56:57], v[50:51], v[52:53]
	v_pk_fma_f32 v[52:53], v[50:51], v[52:53], v[50:51] neg_lo:[1,0,0] neg_hi:[1,0,0]
	v_and_b32_e32 v51, 0xffff0000, v169
	v_cndmask_b32_e32 v58, v53, v57, vcc
	v_cmp_gt_f32_e32 vcc, 0, v50
	v_lshlrev_b32_e32 v50, 16, v169
	v_pk_fma_f32 v[50:51], v[42:43], v[50:51], v[54:55]
	v_cndmask_b32_e32 v59, v52, v56, vcc
	v_fma_f32 v52, |v50|, s21, 1.0
	v_fma_f32 v53, |v51|, s21, 1.0
	v_rcp_f32_e32 v52, v52
	v_rcp_f32_e32 v53, v53
	v_pk_mul_f32 v[54:55], v[50:51], v[50:51]
	v_cmp_gt_f32_e32 vcc, 0, v51
	v_mul_f32_e32 v54, 0xbf38aa3b, v54
	v_pk_fma_f32 v[56:57], v[52:53], s[2:3], v[48:49] op_sel_hi:[1,0,0]
	v_mul_f32_e32 v55, 0xbf38aa3b, v55
	v_exp_f32_e32 v54, v54
	v_pk_fma_f32 v[56:57], v[52:53], v[56:57], s[8:9] op_sel_hi:[1,1,0]
	v_exp_f32_e32 v55, v55
	v_pk_fma_f32 v[56:57], v[52:53], v[56:57], s[20:21] op_sel_hi:[1,1,0]
	v_mov_b64_e32 v[168:169], v[178:179]
	v_pk_fma_f32 v[56:57], v[52:53], v[56:57], s[22:23] op_sel_hi:[1,1,0]
	s_nop 0
	v_pk_mul_f32 v[52:53], v[52:53], v[56:57]
	s_nop 0
	v_pk_mul_f32 v[52:53], v[54:55], v[52:53]
	s_nop 0
	v_pk_mul_f32 v[54:55], v[50:51], v[52:53]
	v_pk_fma_f32 v[52:53], v[50:51], v[52:53], v[50:51] neg_lo:[1,0,0] neg_hi:[1,0,0]
	s_nop 0
	v_cndmask_b32_e32 v51, v53, v55, vcc
	v_cmp_gt_f32_e32 vcc, 0, v50
	v_cvt_pk_bf16_f32 v50, v59, v58
	s_nop 0
	v_cndmask_b32_e32 v52, v52, v54, vcc
	v_cvt_pk_bf16_f32 v51, v52, v51
	v_add_u32_e32 v52, 32, v166
	v_ashrrev_i32_e32 v53, 31, v52
	v_lshlrev_b64 v[52:53], 11, v[52:53]
	v_lshl_add_u64 v[52:53], v[154:155], 0, v[52:53]
	global_store_dwordx2 v[52:53], v[50:51], off
	v_lshlrev_b32_e32 v50, 16, v116
	v_and_b32_e32 v51, 0xffff0000, v116
	v_pk_fma_f32 v[44:45], v[40:41], v[50:51], v[44:45]
	s_nop 0
	v_fma_f32 v50, |v44|, s21, 1.0
	v_fma_f32 v51, |v45|, s21, 1.0
	v_rcp_f32_e32 v50, v50
	v_rcp_f32_e32 v51, v51
	v_pk_mul_f32 v[52:53], v[44:45], v[44:45]
	v_cmp_gt_f32_e32 vcc, 0, v45
	v_mul_f32_e32 v52, 0xbf38aa3b, v52
	v_pk_fma_f32 v[54:55], v[50:51], s[2:3], v[48:49] op_sel_hi:[1,0,0]
	v_mul_f32_e32 v53, 0xbf38aa3b, v53
	v_exp_f32_e32 v52, v52
	v_pk_fma_f32 v[54:55], v[50:51], v[54:55], s[8:9] op_sel_hi:[1,1,0]
	v_exp_f32_e32 v53, v53
	v_pk_fma_f32 v[54:55], v[50:51], v[54:55], s[20:21] op_sel_hi:[1,1,0]
	s_nop 0
	v_pk_fma_f32 v[54:55], v[50:51], v[54:55], s[22:23] op_sel_hi:[1,1,0]
	s_nop 0
	v_pk_mul_f32 v[50:51], v[50:51], v[54:55]
	s_nop 0
	v_pk_mul_f32 v[50:51], v[52:53], v[50:51]
	s_nop 0
	v_pk_mul_f32 v[52:53], v[44:45], v[50:51]
	v_pk_fma_f32 v[50:51], v[44:45], v[50:51], v[44:45] neg_lo:[1,0,0] neg_hi:[1,0,0]
	v_and_b32_e32 v45, 0xffff0000, v117
	v_cndmask_b32_e32 v53, v51, v53, vcc
	v_cmp_gt_f32_e32 vcc, 0, v44
	v_lshlrev_b32_e32 v44, 16, v117
	v_pk_fma_f32 v[44:45], v[42:43], v[44:45], v[46:47]
	v_cndmask_b32_e32 v52, v50, v52, vcc
	v_fma_f32 v46, |v44|, s21, 1.0
	v_fma_f32 v47, |v45|, s21, 1.0
	v_rcp_f32_e32 v46, v46
	v_rcp_f32_e32 v47, v47
	v_pk_mul_f32 v[50:51], v[44:45], v[44:45]
	v_cmp_gt_f32_e32 vcc, 0, v45
	v_mul_f32_e32 v50, 0xbf38aa3b, v50
	v_pk_fma_f32 v[48:49], v[46:47], s[2:3], v[48:49] op_sel_hi:[1,0,0]
	v_mul_f32_e32 v51, 0xbf38aa3b, v51
	v_exp_f32_e32 v50, v50
	v_pk_fma_f32 v[48:49], v[46:47], v[48:49], s[8:9] op_sel_hi:[1,1,0]
	v_exp_f32_e32 v51, v51
	v_pk_fma_f32 v[48:49], v[46:47], v[48:49], s[20:21] op_sel_hi:[1,1,0]
	v_mov_b64_e32 v[116:117], v[180:181]
	v_pk_fma_f32 v[48:49], v[46:47], v[48:49], s[22:23] op_sel_hi:[1,1,0]
	s_nop 0
	v_pk_mul_f32 v[46:47], v[46:47], v[48:49]
	s_nop 0
	v_pk_mul_f32 v[46:47], v[50:51], v[46:47]
	s_nop 0
	v_pk_mul_f32 v[48:49], v[44:45], v[46:47]
	v_pk_fma_f32 v[46:47], v[44:45], v[46:47], v[44:45] neg_lo:[1,0,0] neg_hi:[1,0,0]
	s_nop 0
	v_cndmask_b32_e32 v45, v47, v49, vcc
	v_cmp_gt_f32_e32 vcc, 0, v44
	v_cvt_pk_bf16_f32 v44, v52, v53
	s_nop 0
	v_cndmask_b32_e32 v46, v46, v48, vcc
	v_cvt_pk_bf16_f32 v45, v46, v45
	v_add_u32_e32 v46, 48, v166
	v_ashrrev_i32_e32 v47, 31, v46
	v_lshlrev_b64 v[46:47], 11, v[46:47]
	v_lshl_add_u64 v[46:47], v[154:155], 0, v[46:47]
	v_add_u32_e32 v166, s3, v166
	s_andn2_b64 vcc, exec, s[24:25]
	global_store_dwordx2 v[46:47], v[44:45], off
	s_cbranch_vccz .LBB0_762
